# v29 + attention tile loops: the 16 (8) QK^T MFMAs of tile t are interleaved with the softmax-finish VALU of tile t-1 (disjoint registers) instead of running as two separate segments
# baseline (speedup 1.0000x reference)
.LBB0_645:
	v_add_u32_e32 v218, s11, v192
	v_add_u32_e32 v81, 1, v218
	v_mad_i64_i32 v[82:83], s[0:1], v81, s33, v[164:165]
	v_add_u32_e32 v86, 33, v218
	v_mad_i64_i32 v[84:85], s[0:1], v86, s33, v[164:165]
	global_load_dwordx4 v[146:149], v[82:83], off
	global_load_dwordx4 v[150:153], v[84:85], off
	v_mad_i64_i32 v[82:83], s[0:1], v81, s33, v[166:167]
	v_mad_i64_i32 v[84:85], s[0:1], v86, s33, v[166:167]
	global_load_dwordx4 v[154:157], v[82:83], off
	global_load_dwordx4 v[158:161], v[84:85], off
	ds_read_b128 v[228:231], v191 offset:49152
	ds_read_b128 v[232:235], v190 offset:49152
	ds_read_b128 v[236:239], v191 offset:57344
	ds_read_b128 v[248:251], v190 offset:57344
	ds_read_b128 v[252:255], v189 offset:49152
	s_waitcnt lgkmcnt(4)
	v_mfma_f32_32x32x16_bf16 v[98:113], v[228:231], v[142:145], 0
	ds_read_b128 v[228:231], v189 offset:57344
	v_exp_f32_e32 v226, v66
	v_add_f32_e32 v66, 0, v215
	v_add_f32_e32 v66, v217, v66
	v_add_f32_e32 v66, v213, v66
	v_add_f32_e32 v66, v216, v66
	s_waitcnt lgkmcnt(4)
	v_mfma_f32_32x32x16_bf16 v[98:113], v[232:235], v[138:141], v[98:113]
	ds_read_b128 v[232:235], v188 offset:49152
	v_add_f32_e32 v66, v211, v66
	v_add_f32_e32 v66, v214, v66
	v_add_f32_e32 v66, v210, v66
	v_add_f32_e32 v66, v212, v66
	v_add_f32_e32 v66, v207, v66
	s_waitcnt lgkmcnt(4)
	v_mfma_f32_32x32x16_bf16 v[82:97], v[236:239], v[142:145], 0
	ds_read_b128 v[236:239], v188 offset:57344
	v_add_f32_e32 v66, v209, v66
	v_add_f32_e32 v66, v205, v66
	v_add_f32_e32 v66, v208, v66
	v_exp_f32_e32 v80, v80
	v_add_f32_e32 v66, v203, v66
	s_waitcnt lgkmcnt(4)
	v_mfma_f32_32x32x16_bf16 v[82:97], v[248:251], v[138:141], v[82:97]
	ds_read_b128 v[248:251], v191 offset:49280
	v_exp_f32_e32 v1, v1
	v_add_f32_e32 v66, v206, v66
	v_exp_f32_e32 v78, v78
	v_add_f32_e32 v66, v202, v66
	v_exp_f32_e32 v79, v79
	s_waitcnt lgkmcnt(4)
	v_mfma_f32_32x32x16_bf16 v[98:113], v[252:255], v[134:137], v[98:113]
	ds_read_b128 v[252:255], v191 offset:57472
	v_add_f32_e32 v66, v204, v66
	v_exp_f32_e32 v76, v76
	v_add_f32_e32 v66, v80, v66
	v_exp_f32_e32 v77, v77
	v_add_f32_e32 v66, v1, v66
	s_waitcnt lgkmcnt(4)
	v_mfma_f32_32x32x16_bf16 v[82:97], v[228:231], v[134:137], v[82:97]
	ds_read_b128 v[228:231], v190 offset:49280
	v_exp_f32_e32 v81, v74
	v_add_f32_e32 v66, v78, v66
	v_exp_f32_e32 v219, v75
	v_add_f32_e32 v66, v79, v66
	v_exp_f32_e32 v220, v72
	s_waitcnt lgkmcnt(4)
	v_mfma_f32_32x32x16_bf16 v[98:113], v[232:235], v[130:133], v[98:113]
	ds_read_b128 v[232:235], v190 offset:57472
	v_add_f32_e32 v66, v76, v66
	v_exp_f32_e32 v221, v73
	v_add_f32_e32 v66, v77, v66
	v_exp_f32_e32 v222, v70
	v_add_f32_e32 v66, v81, v66
	s_waitcnt lgkmcnt(4)
	v_mfma_f32_32x32x16_bf16 v[82:97], v[236:239], v[130:133], v[82:97]
	ds_read_b128 v[236:239], v189 offset:49280
	v_exp_f32_e32 v223, v71
	v_add_f32_e32 v66, v219, v66
	v_exp_f32_e32 v224, v68
	v_add_f32_e32 v66, v220, v66
	v_exp_f32_e32 v225, v69
	s_waitcnt lgkmcnt(4)
	v_mfma_f32_32x32x16_bf16 v[98:113], v[248:251], v[126:129], v[98:113]
	ds_read_b128 v[248:251], v189 offset:57472
	v_add_f32_e32 v66, v221, v66
	v_add_f32_e32 v66, v222, v66
	v_exp_f32_e32 v227, v67
	v_add_f32_e32 v66, v223, v66
	v_add_f32_e32 v66, v224, v66
	s_waitcnt lgkmcnt(4)
	v_mfma_f32_32x32x16_bf16 v[82:97], v[252:255], v[126:129], v[82:97]
	ds_read_b128 v[252:255], v188 offset:49280
	v_add_f32_e32 v66, v225, v66
	v_add_f32_e32 v66, v226, v66
	v_add_f32_e32 v200, v227, v66
	v_mov_b32_e32 v201, v200
	v_cvt_pk_bf16_f32 v66, v215, v217
	s_waitcnt lgkmcnt(4)
	v_mfma_f32_32x32x16_bf16 v[98:113], v[228:231], v[122:125], v[98:113]
	ds_read_b128 v[228:231], v188 offset:57472
	v_cvt_pk_bf16_f32 v67, v213, v216
	v_cvt_pk_bf16_f32 v68, v211, v214
	v_cvt_pk_bf16_f32 v69, v210, v212
	v_cvt_pk_bf16_f32 v70, v207, v209
	v_cvt_pk_bf16_f32 v71, v205, v208
	s_waitcnt lgkmcnt(4)
	v_mfma_f32_32x32x16_bf16 v[82:97], v[232:235], v[122:125], v[82:97]
	v_cvt_pk_bf16_f32 v72, v203, v206
	v_cvt_pk_bf16_f32 v73, v202, v204
	v_cvt_pk_bf16_f32 v74, v80, v1
	v_cvt_pk_bf16_f32 v75, v78, v79
	v_cvt_pk_bf16_f32 v76, v76, v77
	s_waitcnt lgkmcnt(3)
	v_mfma_f32_32x32x16_bf16 v[98:113], v[236:239], v[118:121], v[98:113]
	v_cvt_pk_bf16_f32 v77, v81, v219
	v_cvt_pk_bf16_f32 v78, v220, v221
	v_cvt_pk_bf16_f32 v79, v222, v223
	v_cvt_pk_bf16_f32 v80, v224, v225
	v_cvt_pk_bf16_f32 v81, v226, v227
	s_waitcnt lgkmcnt(2)
	v_mfma_f32_32x32x16_bf16 v[82:97], v[248:251], v[118:121], v[82:97]
	s_nop 1
	v_permlane32_swap_b32_e32 v200, v201
	v_permlane32_swap_b32_e32 v66, v68
	v_permlane32_swap_b32_e32 v67, v69
	v_permlane32_swap_b32_e32 v70, v72
	s_waitcnt lgkmcnt(1)
	v_mfma_f32_32x32x16_bf16 v[98:113], v[252:255], v[114:117], v[98:113]
	v_permlane32_swap_b32_e32 v71, v73
	v_permlane32_swap_b32_e32 v74, v76
	v_permlane32_swap_b32_e32 v75, v77
	v_permlane32_swap_b32_e32 v78, v80
	v_permlane32_swap_b32_e32 v79, v81
	s_waitcnt lgkmcnt(0)
	v_mfma_f32_32x32x16_bf16 v[82:97], v[228:231], v[114:117], v[82:97]
	ds_read_b64_tr_b16 v[202:203], v183 offset:0
	ds_read_b64_tr_b16 v[204:205], v183 offset:0x800
	ds_read_b64_tr_b16 v[206:207], v183 offset:0x1000
	ds_read_b64_tr_b16 v[208:209], v183 offset:0x1800
	ds_read_b64_tr_b16 v[210:211], v183 offset:0x2000
	ds_read_b64_tr_b16 v[212:213], v183 offset:0x2800
	ds_read_b64_tr_b16 v[214:215], v183 offset:0x3000
	ds_read_b64_tr_b16 v[216:217], v183 offset:0x3800
	s_nop 0
	s_waitcnt lgkmcnt(6)
	v_mfma_f32_32x32x16_bf16 v[50:65], v[66:69], v[202:205], v[50:65]
	ds_read_b64_tr_b16 v[202:203], v183 offset:0x200
	ds_read_b64_tr_b16 v[204:205], v183 offset:0xa00
	s_waitcnt lgkmcnt(6)
	v_mfma_f32_32x32x16_bf16 v[50:65], v[70:73], v[206:209], v[50:65]
	ds_read_b64_tr_b16 v[206:207], v183 offset:0x1200
	ds_read_b64_tr_b16 v[208:209], v183 offset:0x1a00
	s_waitcnt lgkmcnt(6)
	v_mfma_f32_32x32x16_bf16 v[50:65], v[74:77], v[210:213], v[50:65]
	ds_read_b64_tr_b16 v[210:211], v183 offset:0x2200
	ds_read_b64_tr_b16 v[212:213], v183 offset:0x2a00
	s_waitcnt lgkmcnt(6)
	v_mfma_f32_32x32x16_bf16 v[50:65], v[78:81], v[214:217], v[50:65]
	ds_read_b64_tr_b16 v[214:215], v183 offset:0x3200
	ds_read_b64_tr_b16 v[216:217], v183 offset:0x3a00
	s_waitcnt lgkmcnt(6)
	v_mfma_f32_32x32x16_bf16 v[34:49], v[66:69], v[202:205], v[34:49]
	ds_read_b64_tr_b16 v[202:203], v183 offset:0x400
	ds_read_b64_tr_b16 v[204:205], v183 offset:0xc00
	s_waitcnt lgkmcnt(6)
	v_mfma_f32_32x32x16_bf16 v[34:49], v[70:73], v[206:209], v[34:49]
	ds_read_b64_tr_b16 v[206:207], v183 offset:0x1400
	ds_read_b64_tr_b16 v[208:209], v183 offset:0x1c00
	s_waitcnt lgkmcnt(6)
	v_mfma_f32_32x32x16_bf16 v[34:49], v[74:77], v[210:213], v[34:49]
	ds_read_b64_tr_b16 v[210:211], v183 offset:0x2400
	ds_read_b64_tr_b16 v[212:213], v183 offset:0x2c00
	s_waitcnt lgkmcnt(6)
	v_mfma_f32_32x32x16_bf16 v[34:49], v[78:81], v[214:217], v[34:49]
	ds_read_b64_tr_b16 v[214:215], v183 offset:0x3400
	ds_read_b64_tr_b16 v[216:217], v183 offset:0x3c00
	s_waitcnt lgkmcnt(6)
	v_mfma_f32_32x32x16_bf16 v[18:33], v[66:69], v[202:205], v[18:33]
	ds_read_b64_tr_b16 v[202:203], v183 offset:0x600
	ds_read_b64_tr_b16 v[204:205], v183 offset:0xe00
	s_waitcnt lgkmcnt(6)
	v_mfma_f32_32x32x16_bf16 v[18:33], v[70:73], v[206:209], v[18:33]
	ds_read_b64_tr_b16 v[206:207], v183 offset:0x1600
	ds_read_b64_tr_b16 v[208:209], v183 offset:0x1e00
	s_waitcnt lgkmcnt(6)
	v_mfma_f32_32x32x16_bf16 v[18:33], v[74:77], v[210:213], v[18:33]
	ds_read_b64_tr_b16 v[210:211], v183 offset:0x2600
	ds_read_b64_tr_b16 v[212:213], v183 offset:0x2e00
	s_waitcnt lgkmcnt(6)
	v_mfma_f32_32x32x16_bf16 v[18:33], v[78:81], v[214:217], v[18:33]
	ds_read_b64_tr_b16 v[214:215], v183 offset:0x3600
	ds_read_b64_tr_b16 v[216:217], v183 offset:0x3e00
	s_waitcnt lgkmcnt(6)
	v_mfma_f32_32x32x16_bf16 v[2:17], v[66:69], v[202:205], v[2:17]
	s_waitcnt lgkmcnt(4)
	v_mfma_f32_32x32x16_bf16 v[2:17], v[70:73], v[206:209], v[2:17]
	s_waitcnt lgkmcnt(2)
	v_mfma_f32_32x32x16_bf16 v[2:17], v[74:77], v[210:213], v[2:17]
	s_waitcnt lgkmcnt(0)
	v_mfma_f32_32x32x16_bf16 v[2:17], v[78:81], v[214:217], v[2:17]
	ds_read_b128 v[66:69], v198
	ds_read_b128 v[70:73], v198 offset:32
	ds_read_b128 v[202:205], v198 offset:128
	ds_read_b128 v[206:209], v198 offset:160
	ds_read_b128 v[76:79], v198 offset:64
	ds_read_b128 v[210:213], v198 offset:96
	ds_read_b128 v[214:217], v198 offset:192
	ds_read_b128 v[220:223], v198 offset:224
	s_waitcnt lgkmcnt(7)
	v_xor_b32_e32 v69, 0x80000000, v69
	s_waitcnt lgkmcnt(3)
	v_xor_b32_e32 v225, 0x80000000, v79
	v_xor_b32_e32 v224, 0x80000000, v78
	v_xor_b32_e32 v68, 0x80000000, v68
	v_xor_b32_e32 v73, 0x80000000, v73
	v_xor_b32_e32 v72, 0x80000000, v72
	s_waitcnt lgkmcnt(2)
	v_xor_b32_e32 v81, 0x80000000, v213
	v_xor_b32_e32 v80, 0x80000000, v212
	v_pk_fma_f32 v[74:75], v[110:111], s[12:13], v[210:211] op_sel_hi:[1,0,1] neg_lo:[0,0,1] neg_hi:[0,0,1]
	v_pk_fma_f32 v[78:79], v[106:107], s[12:13], v[76:77] op_sel_hi:[1,0,1] neg_lo:[0,0,1] neg_hi:[0,0,1]
	v_pk_fma_f32 v[102:103], v[102:103], s[12:13], v[70:71] op_sel_hi:[1,0,1] neg_lo:[0,0,1] neg_hi:[0,0,1]
	v_pk_fma_f32 v[106:107], v[108:109], s[12:13], v[224:225] op_sel_hi:[1,0,1]
	v_xor_b32_e32 v109, 0x80000000, v205
	v_xor_b32_e32 v108, 0x80000000, v204
	v_xor_b32_e32 v111, 0x80000000, v209
	v_xor_b32_e32 v110, 0x80000000, v208
	s_waitcnt lgkmcnt(1)
	v_xor_b32_e32 v77, 0x80000000, v217
	v_xor_b32_e32 v76, 0x80000000, v216
	s_waitcnt lgkmcnt(0)
	v_xor_b32_e32 v71, 0x80000000, v223
	v_xor_b32_e32 v70, 0x80000000, v222
	v_pk_fma_f32 v[80:81], v[112:113], s[12:13], v[80:81] op_sel_hi:[1,0,1]
	v_pk_fma_f32 v[104:105], v[104:105], s[12:13], v[72:73] op_sel_hi:[1,0,1]
	v_pk_fma_f32 v[100:101], v[100:101], s[12:13], v[68:69] op_sel_hi:[1,0,1]
	v_pk_fma_f32 v[98:99], v[98:99], s[12:13], v[66:67] op_sel_hi:[1,0,1] neg_lo:[0,0,1] neg_hi:[0,0,1]
	v_pk_fma_f32 v[66:67], v[94:95], s[12:13], v[220:221] op_sel_hi:[1,0,1] neg_lo:[0,0,1] neg_hi:[0,0,1]
	v_pk_fma_f32 v[68:69], v[90:91], s[12:13], v[214:215] op_sel_hi:[1,0,1] neg_lo:[0,0,1] neg_hi:[0,0,1]
	v_pk_fma_f32 v[72:73], v[86:87], s[12:13], v[206:207] op_sel_hi:[1,0,1] neg_lo:[0,0,1] neg_hi:[0,0,1]
	v_pk_fma_f32 v[70:71], v[96:97], s[12:13], v[70:71] op_sel_hi:[1,0,1]
	v_pk_fma_f32 v[76:77], v[92:93], s[12:13], v[76:77] op_sel_hi:[1,0,1]
	v_pk_fma_f32 v[86:87], v[88:89], s[12:13], v[110:111] op_sel_hi:[1,0,1]
	v_pk_fma_f32 v[84:85], v[84:85], s[12:13], v[108:109] op_sel_hi:[1,0,1]
	s_cmp_le_i32 s11, s27
	v_pk_fma_f32 v[82:83], v[82:83], s[12:13], v[202:203] op_sel_hi:[1,0,1] neg_lo:[0,0,1] neg_hi:[0,0,1]
	s_cbranch_scc1 .LBB0_647
	v_add_u32_e32 v1, 64, v199
	v_cmp_gt_i32_e64 s[92:93], 26, v1
	v_cmp_gt_i32_e64 s[94:95], 27, v1
	v_cmp_gt_i32_e64 s[90:91], 25, v1
	s_and_b64 s[92:93], s[94:95], s[92:93]
	v_cmp_gt_i32_e64 s[88:89], 24, v1
	s_and_b64 s[90:91], s[92:93], s[90:91]
	v_cmp_gt_i32_e64 s[86:87], 19, v1
	s_and_b64 s[88:89], s[90:91], s[88:89]
	v_cmp_gt_i32_e64 s[84:85], 18, v1
	s_and_b64 s[86:87], s[88:89], s[86:87]
	v_cmp_gt_i32_e64 s[82:83], 17, v1
	s_and_b64 s[84:85], s[86:87], s[84:85]
	v_cmp_gt_i32_e64 s[80:81], 16, v1
	s_and_b64 s[82:83], s[84:85], s[82:83]
	v_cmp_gt_i32_e64 s[78:79], 11, v1
	s_and_b64 s[80:81], s[82:83], s[80:81]
	v_cmp_gt_i32_e64 s[76:77], 10, v1
	s_and_b64 s[78:79], s[80:81], s[78:79]
	v_cmp_gt_i32_e64 s[74:75], 9, v1
	s_and_b64 s[76:77], s[78:79], s[76:77]
	v_cmp_gt_i32_e64 s[72:73], 8, v1
	s_and_b64 s[74:75], s[76:77], s[74:75]
	v_cmp_gt_i32_e64 s[70:71], 3, v1
	s_and_b64 s[72:73], s[74:75], s[72:73]
	v_cmp_gt_i32_e64 s[68:69], 2, v1
	s_and_b64 s[70:71], s[72:73], s[70:71]
	v_cmp_gt_i32_e64 s[2:3], 1, v1
	s_and_b64 s[68:69], s[70:71], s[68:69]
	v_cmp_gt_i32_e64 s[0:1], 0, v1
	s_and_b64 s[2:3], s[68:69], s[2:3]
	s_and_b64 s[0:1], s[2:3], s[0:1]
	v_cmp_gt_i32_e64 s[66:67], 58, v1
	v_cndmask_b32_e64 v98, v98, v175, s[0:1]
	v_cmp_gt_i32_e64 s[0:1], 59, v1
	v_cmp_gt_i32_e64 s[64:65], 57, v1
	v_cmp_gt_i32_e64 s[62:63], 56, v1
	v_cndmask_b32_e64 v71, v71, v175, s[0:1]
	s_and_b64 s[0:1], s[0:1], s[66:67]
	v_cndmask_b32_e64 v70, v70, v175, s[0:1]
	s_and_b64 s[0:1], s[0:1], s[64:65]
	v_cmp_gt_i32_e64 s[60:61], 51, v1
	v_cndmask_b32_e64 v67, v67, v175, s[0:1]
	s_and_b64 s[0:1], s[0:1], s[62:63]
	v_cmp_gt_i32_e64 s[58:59], 50, v1
	v_cndmask_b32_e64 v66, v66, v175, s[0:1]
	s_and_b64 s[0:1], s[0:1], s[60:61]
	v_cmp_gt_i32_e64 s[56:57], 49, v1
	v_cndmask_b32_e64 v77, v77, v175, s[0:1]
	s_and_b64 s[0:1], s[0:1], s[58:59]
	v_cmp_gt_i32_e64 s[54:55], 48, v1
	v_cndmask_b32_e64 v76, v76, v175, s[0:1]
	s_and_b64 s[0:1], s[0:1], s[56:57]
	v_cmp_gt_i32_e64 s[52:53], 43, v1
	v_cndmask_b32_e64 v69, v69, v175, s[0:1]
	s_and_b64 s[0:1], s[0:1], s[54:55]
	v_cmp_gt_i32_e64 s[50:51], 42, v1
	v_cndmask_b32_e64 v68, v68, v175, s[0:1]
	s_and_b64 s[0:1], s[0:1], s[52:53]
	v_cmp_gt_i32_e64 s[48:49], 41, v1
	v_cndmask_b32_e64 v87, v87, v175, s[0:1]
	s_and_b64 s[0:1], s[0:1], s[50:51]
	v_cmp_gt_i32_e64 s[46:47], 40, v1
	v_cndmask_b32_e64 v86, v86, v175, s[0:1]
	s_and_b64 s[0:1], s[0:1], s[48:49]
	v_cmp_gt_i32_e64 s[44:45], 35, v1
	v_cndmask_b32_e64 v73, v73, v175, s[0:1]
	s_and_b64 s[0:1], s[0:1], s[46:47]
	v_cmp_gt_i32_e64 s[42:43], 34, v1
	v_cndmask_b32_e64 v72, v72, v175, s[0:1]
	s_and_b64 s[0:1], s[0:1], s[44:45]
	v_cmp_gt_i32_e64 s[40:41], 33, v1
	v_cndmask_b32_e64 v85, v85, v175, s[0:1]
	s_and_b64 s[0:1], s[0:1], s[42:43]
	v_cmp_gt_i32_e32 vcc, 32, v1
	v_cndmask_b32_e64 v84, v84, v175, s[0:1]
	s_and_b64 s[0:1], s[0:1], s[40:41]
	v_cndmask_b32_e64 v74, v74, v175, s[88:89]
	v_readlane_b32 s88, v242, 2
	s_and_b64 vcc, s[0:1], vcc
	v_cndmask_b32_e64 v81, v81, v175, s[94:95]
	v_cndmask_b32_e64 v80, v80, v175, s[92:93]
	s_movk_i32 s93, 0x6018
	s_mov_b32 s92, 0xf800000
	v_cndmask_b32_e64 v75, v75, v175, s[90:91]
	s_mov_b64 s[90:91], s[16:17]
	v_readlane_b32 s89, v242, 3
	v_cndmask_b32_e64 v107, v107, v175, s[86:87]
	v_readlane_b32 s86, v242, 0
	v_cndmask_b32_e64 v106, v106, v175, s[84:85]
	v_cndmask_b32_e64 v79, v79, v175, s[82:83]
	s_movk_i32 s83, 0x6000
	v_cndmask_b32_e64 v78, v78, v175, s[80:81]
	v_cndmask_b32_e64 v105, v105, v175, s[78:79]
	v_cndmask_b32_e64 v104, v104, v175, s[76:77]
	v_cndmask_b32_e64 v103, v103, v175, s[74:75]
	v_cndmask_b32_e64 v102, v102, v175, s[72:73]
	v_cndmask_b32_e64 v101, v101, v175, s[70:71]
	v_cndmask_b32_e64 v100, v100, v175, s[68:69]
	v_cndmask_b32_e64 v99, v99, v175, s[2:3]
	s_mov_b32 s56, s30
	v_cndmask_b32_e64 v83, v83, v175, s[0:1]
	v_cndmask_b32_e32 v82, v82, v175, vcc
	v_readlane_b32 s87, v242, 1

.LBB0_653:
	v_sub_f32_e32 v104, v82, v1
	v_sub_f32_e32 v105, v83, v1
	v_sub_f32_e32 v208, v84, v1
	v_sub_f32_e32 v209, v85, v1
	v_sub_f32_e32 v210, v72, v1
	v_sub_f32_e32 v211, v73, v1
	v_sub_f32_e32 v212, v86, v1
	v_sub_f32_e32 v213, v87, v1
	v_sub_f32_e32 v214, v68, v1
	v_sub_f32_e32 v215, v69, v1
	v_sub_f32_e32 v216, v76, v1
	v_sub_f32_e32 v217, v77, v1
	v_sub_f32_e32 v218, v66, v1
	v_sub_f32_e32 v219, v67, v1
	v_sub_f32_e32 v220, v70, v1
	v_sub_f32_e32 v221, v71, v1
	ds_read_b128 v[228:231], v191 offset:32768
	ds_read_b128 v[232:235], v190 offset:32768
	ds_read_b128 v[236:239], v191 offset:40960
	ds_read_b128 v[248:251], v190 offset:40960
	ds_read_b128 v[252:255], v189 offset:32768
	s_waitcnt lgkmcnt(4)
	v_mfma_f32_32x32x16_bf16 v[82:97], v[228:231], v[142:145], 0
	ds_read_b128 v[228:231], v189 offset:40960
	v_exp_f32_e32 v222, v104
	v_add_f32_e32 v104, 0, v196
	v_add_f32_e32 v104, v203, v104
	v_add_f32_e32 v104, v112, v104
	v_add_f32_e32 v104, v202, v104
	s_waitcnt lgkmcnt(4)
	v_mfma_f32_32x32x16_bf16 v[82:97], v[232:235], v[138:141], v[82:97]
	ds_read_b128 v[232:235], v188 offset:32768
	v_add_f32_e32 v104, v110, v104
	v_add_f32_e32 v104, v113, v104
	v_add_f32_e32 v104, v109, v104
	v_add_f32_e32 v104, v111, v104
	v_add_f32_e32 v104, v103, v104
	s_waitcnt lgkmcnt(4)
	v_mfma_f32_32x32x16_bf16 v[66:81], v[236:239], v[142:145], 0
	ds_read_b128 v[236:239], v188 offset:40960
	v_add_f32_e32 v104, v107, v104
	v_add_f32_e32 v104, v101, v104
	v_add_f32_e32 v104, v106, v104
	v_add_f32_e32 v104, v99, v104
	v_exp_f32_e32 v223, v105
	s_waitcnt lgkmcnt(4)
	v_mfma_f32_32x32x16_bf16 v[66:81], v[248:251], v[138:141], v[66:81]
	ds_read_b128 v[248:251], v191 offset:32896
	v_add_f32_e32 v104, v102, v104
	v_exp_f32_e32 v208, v208
	v_add_f32_e32 v104, v98, v104
	v_exp_f32_e32 v209, v209
	v_add_f32_e32 v104, v100, v104
	s_waitcnt lgkmcnt(4)
	v_mfma_f32_32x32x16_bf16 v[82:97], v[252:255], v[134:137], v[82:97]
	ds_read_b128 v[252:255], v191 offset:41088
	v_exp_f32_e32 v210, v210
	v_add_f32_e32 v104, v222, v104
	v_exp_f32_e32 v211, v211
	v_add_f32_e32 v104, v223, v104
	v_exp_f32_e32 v212, v212
	s_waitcnt lgkmcnt(4)
	v_mfma_f32_32x32x16_bf16 v[66:81], v[228:231], v[134:137], v[66:81]
	ds_read_b128 v[228:231], v190 offset:32896
	v_add_f32_e32 v104, v208, v104
	v_exp_f32_e32 v213, v213
	v_add_f32_e32 v104, v209, v104
	v_exp_f32_e32 v214, v214
	v_add_f32_e32 v104, v210, v104
	s_waitcnt lgkmcnt(4)
	v_mfma_f32_32x32x16_bf16 v[82:97], v[232:235], v[130:133], v[82:97]
	ds_read_b128 v[232:235], v190 offset:41088
	v_exp_f32_e32 v215, v215
	v_add_f32_e32 v104, v211, v104
	v_exp_f32_e32 v216, v216
	v_add_f32_e32 v104, v212, v104
	v_exp_f32_e32 v217, v217
	s_waitcnt lgkmcnt(4)
	v_mfma_f32_32x32x16_bf16 v[66:81], v[236:239], v[130:133], v[66:81]
	ds_read_b128 v[236:239], v189 offset:32896
	v_add_f32_e32 v104, v213, v104
	v_exp_f32_e32 v218, v218
	v_add_f32_e32 v104, v214, v104
	v_exp_f32_e32 v219, v219
	v_add_f32_e32 v104, v215, v104
	s_waitcnt lgkmcnt(4)
	v_mfma_f32_32x32x16_bf16 v[82:97], v[248:251], v[126:129], v[82:97]
	ds_read_b128 v[248:251], v189 offset:41088
	v_exp_f32_e32 v220, v220
	v_add_f32_e32 v104, v216, v104
	v_exp_f32_e32 v221, v221
	v_add_f32_e32 v104, v217, v104
	v_add_f32_e32 v104, v218, v104
	s_waitcnt lgkmcnt(4)
	v_mfma_f32_32x32x16_bf16 v[66:81], v[252:255], v[126:129], v[66:81]
	ds_read_b128 v[252:255], v188 offset:32896
	v_add_f32_e32 v104, v219, v104
	v_add_f32_e32 v104, v220, v104
	v_add_f32_e32 v104, v221, v104
	v_mov_b32_e32 v105, v104
	v_cvt_pk_bf16_f32 v204, v196, v203
	s_waitcnt lgkmcnt(4)
	v_mfma_f32_32x32x16_bf16 v[82:97], v[228:231], v[122:125], v[82:97]
	ds_read_b128 v[228:231], v188 offset:41088
	v_cvt_pk_bf16_f32 v205, v112, v202
	v_cvt_pk_bf16_f32 v206, v110, v113
	v_cvt_pk_bf16_f32 v207, v109, v111
	v_cvt_pk_bf16_f32 v110, v103, v107
	v_cvt_pk_bf16_f32 v111, v101, v106
	s_waitcnt lgkmcnt(4)
	v_mfma_f32_32x32x16_bf16 v[66:81], v[232:235], v[122:125], v[66:81]
	v_cvt_pk_bf16_f32 v112, v99, v102
	v_cvt_pk_bf16_f32 v113, v98, v100
	v_cvt_pk_bf16_f32 v98, v222, v223
	v_cvt_pk_bf16_f32 v99, v208, v209
	v_cvt_pk_bf16_f32 v100, v210, v211
	s_waitcnt lgkmcnt(3)
	v_mfma_f32_32x32x16_bf16 v[82:97], v[236:239], v[118:121], v[82:97]
	v_cvt_pk_bf16_f32 v101, v212, v213
	s_nop 1
	v_permlane32_swap_b32_e32 v104, v105
	v_permlane32_swap_b32_e32 v98, v100
	v_permlane32_swap_b32_e32 v99, v101
	s_waitcnt lgkmcnt(2)
	v_mfma_f32_32x32x16_bf16 v[66:81], v[248:251], v[118:121], v[66:81]
	v_cvt_pk_bf16_f32 v208, v214, v215
	v_cvt_pk_bf16_f32 v209, v216, v217
	v_cvt_pk_bf16_f32 v210, v218, v219
	v_cvt_pk_bf16_f32 v211, v220, v221
	v_permlane32_swap_b32_e32 v204, v206
	s_waitcnt lgkmcnt(1)
	v_mfma_f32_32x32x16_bf16 v[82:97], v[252:255], v[114:117], v[82:97]
	v_permlane32_swap_b32_e32 v205, v207
	v_permlane32_swap_b32_e32 v110, v112
	v_permlane32_swap_b32_e32 v111, v113
	v_permlane32_swap_b32_e32 v208, v210
	v_permlane32_swap_b32_e32 v209, v211
	s_waitcnt lgkmcnt(0)
	v_mfma_f32_32x32x16_bf16 v[66:81], v[228:231], v[114:117], v[66:81]
	ds_read_b64_tr_b16 v[212:213], v183 offset:0x4000
	ds_read_b64_tr_b16 v[214:215], v183 offset:0x4800
	ds_read_b64_tr_b16 v[216:217], v183 offset:0x5000
	ds_read_b64_tr_b16 v[218:219], v183 offset:0x5800
	ds_read_b64_tr_b16 v[220:221], v183 offset:0x6000
	ds_read_b64_tr_b16 v[222:223], v183 offset:0x6800
	ds_read_b64_tr_b16 v[224:225], v183 offset:0x7000
	ds_read_b64_tr_b16 v[226:227], v183 offset:0x7800
	s_nop 0
	s_waitcnt lgkmcnt(6)
	v_mfma_f32_32x32x16_bf16 v[50:65], v[204:207], v[212:215], v[50:65]
	ds_read_b64_tr_b16 v[212:213], v183 offset:0x4200
	ds_read_b64_tr_b16 v[214:215], v183 offset:0x4a00
	s_waitcnt lgkmcnt(6)
	v_mfma_f32_32x32x16_bf16 v[50:65], v[110:113], v[216:219], v[50:65]
	ds_read_b64_tr_b16 v[216:217], v183 offset:0x5200
	ds_read_b64_tr_b16 v[218:219], v183 offset:0x5a00
	s_waitcnt lgkmcnt(6)
	v_mfma_f32_32x32x16_bf16 v[50:65], v[98:101], v[220:223], v[50:65]
	ds_read_b64_tr_b16 v[220:221], v183 offset:0x6200
	ds_read_b64_tr_b16 v[222:223], v183 offset:0x6a00
	s_waitcnt lgkmcnt(6)
	v_mfma_f32_32x32x16_bf16 v[50:65], v[208:211], v[224:227], v[50:65]
	ds_read_b64_tr_b16 v[224:225], v183 offset:0x7200
	ds_read_b64_tr_b16 v[226:227], v183 offset:0x7a00
	s_waitcnt lgkmcnt(6)
	v_mfma_f32_32x32x16_bf16 v[34:49], v[204:207], v[212:215], v[34:49]
	ds_read_b64_tr_b16 v[212:213], v183 offset:0x4400
	ds_read_b64_tr_b16 v[214:215], v183 offset:0x4c00
	s_waitcnt lgkmcnt(6)
	v_mfma_f32_32x32x16_bf16 v[34:49], v[110:113], v[216:219], v[34:49]
	ds_read_b64_tr_b16 v[216:217], v183 offset:0x5400
	ds_read_b64_tr_b16 v[218:219], v183 offset:0x5c00
	s_waitcnt lgkmcnt(6)
	v_mfma_f32_32x32x16_bf16 v[34:49], v[98:101], v[220:223], v[34:49]
	ds_read_b64_tr_b16 v[220:221], v183 offset:0x6400
	ds_read_b64_tr_b16 v[222:223], v183 offset:0x6c00
	s_waitcnt lgkmcnt(6)
	v_mfma_f32_32x32x16_bf16 v[34:49], v[208:211], v[224:227], v[34:49]
	ds_read_b64_tr_b16 v[224:225], v183 offset:0x7400
	ds_read_b64_tr_b16 v[226:227], v183 offset:0x7c00
	s_waitcnt lgkmcnt(6)
	v_mfma_f32_32x32x16_bf16 v[18:33], v[204:207], v[212:215], v[18:33]
	ds_read_b64_tr_b16 v[212:213], v183 offset:0x4600
	ds_read_b64_tr_b16 v[214:215], v183 offset:0x4e00
	s_waitcnt lgkmcnt(6)
	v_mfma_f32_32x32x16_bf16 v[18:33], v[110:113], v[216:219], v[18:33]
	ds_read_b64_tr_b16 v[216:217], v183 offset:0x5600
	ds_read_b64_tr_b16 v[218:219], v183 offset:0x5e00
	s_waitcnt lgkmcnt(6)
	v_mfma_f32_32x32x16_bf16 v[18:33], v[98:101], v[220:223], v[18:33]
	ds_read_b64_tr_b16 v[220:221], v183 offset:0x6600
	ds_read_b64_tr_b16 v[222:223], v183 offset:0x6e00
	s_waitcnt lgkmcnt(6)
	v_mfma_f32_32x32x16_bf16 v[18:33], v[208:211], v[224:227], v[18:33]
	ds_read_b64_tr_b16 v[224:225], v183 offset:0x7600
	ds_read_b64_tr_b16 v[226:227], v183 offset:0x7e00
	s_waitcnt lgkmcnt(6)
	v_mfma_f32_32x32x16_bf16 v[2:17], v[204:207], v[212:215], v[2:17]
	s_waitcnt lgkmcnt(4)
	v_mfma_f32_32x32x16_bf16 v[2:17], v[110:113], v[216:219], v[2:17]
	s_waitcnt lgkmcnt(2)
	v_mfma_f32_32x32x16_bf16 v[2:17], v[98:101], v[220:223], v[2:17]
	s_waitcnt lgkmcnt(0)
	v_mfma_f32_32x32x16_bf16 v[2:17], v[208:211], v[224:227], v[2:17]
	ds_read_b128 v[100:103], v198 offset:256
	ds_read_b128 v[110:113], v198 offset:288
	ds_read_b128 v[202:205], v198 offset:384
	ds_read_b128 v[206:209], v198 offset:416
	ds_read_b128 v[210:213], v198 offset:320
	ds_read_b128 v[214:217], v198 offset:352
	ds_read_b128 v[218:221], v198 offset:448
	ds_read_b128 v[222:225], v198 offset:480
	s_waitcnt lgkmcnt(7)
	v_xor_b32_e32 v103, 0x80000000, v103
	v_xor_b32_e32 v102, 0x80000000, v102
	s_waitcnt lgkmcnt(6)
	v_xor_b32_e32 v107, 0x80000000, v113
	v_xor_b32_e32 v106, 0x80000000, v112
	s_waitcnt lgkmcnt(3)
	v_xor_b32_e32 v113, 0x80000000, v213
	v_xor_b32_e32 v112, 0x80000000, v212
	s_waitcnt lgkmcnt(2)
	v_xor_b32_e32 v213, 0x80000000, v217
	v_xor_b32_e32 v212, 0x80000000, v216
	v_pk_fma_f32 v[98:99], v[86:87], s[12:13], v[110:111] op_sel_hi:[1,0,1] neg_lo:[0,0,1] neg_hi:[0,0,1]
	v_pk_fma_f32 v[86:87], v[96:97], s[12:13], v[212:213] op_sel_hi:[1,0,1]
	v_pk_fma_f32 v[88:89], v[88:89], s[12:13], v[106:107] op_sel_hi:[1,0,1]
	v_pk_fma_f32 v[84:85], v[84:85], s[12:13], v[102:103] op_sel_hi:[1,0,1]
	v_pk_fma_f32 v[96:97], v[82:83], s[12:13], v[100:101] op_sel_hi:[1,0,1] neg_lo:[0,0,1] neg_hi:[0,0,1]
	v_xor_b32_e32 v103, 0x80000000, v205
	v_xor_b32_e32 v102, 0x80000000, v204
	v_xor_b32_e32 v101, 0x80000000, v209
	v_xor_b32_e32 v100, 0x80000000, v208
	s_waitcnt lgkmcnt(1)
	v_xor_b32_e32 v107, 0x80000000, v221
	v_xor_b32_e32 v106, 0x80000000, v220
	s_waitcnt lgkmcnt(0)
	v_xor_b32_e32 v111, 0x80000000, v225
	v_xor_b32_e32 v110, 0x80000000, v224
	s_add_i32 s0, s11, 64
	v_pk_fma_f32 v[94:95], v[94:95], s[12:13], v[214:215] op_sel_hi:[1,0,1] neg_lo:[0,0,1] neg_hi:[0,0,1]
	v_pk_fma_f32 v[90:91], v[90:91], s[12:13], v[210:211] op_sel_hi:[1,0,1] neg_lo:[0,0,1] neg_hi:[0,0,1]
	v_pk_fma_f32 v[92:93], v[92:93], s[12:13], v[112:113] op_sel_hi:[1,0,1]
	v_pk_fma_f32 v[82:83], v[78:79], s[12:13], v[222:223] op_sel_hi:[1,0,1] neg_lo:[0,0,1] neg_hi:[0,0,1]
	v_pk_fma_f32 v[74:75], v[74:75], s[12:13], v[218:219] op_sel_hi:[1,0,1] neg_lo:[0,0,1] neg_hi:[0,0,1]
	v_pk_fma_f32 v[78:79], v[70:71], s[12:13], v[206:207] op_sel_hi:[1,0,1] neg_lo:[0,0,1] neg_hi:[0,0,1]
	v_pk_fma_f32 v[70:71], v[80:81], s[12:13], v[110:111] op_sel_hi:[1,0,1]
	v_pk_fma_f32 v[76:77], v[76:77], s[12:13], v[106:107] op_sel_hi:[1,0,1]
	v_pk_fma_f32 v[100:101], v[72:73], s[12:13], v[100:101] op_sel_hi:[1,0,1]
	v_pk_fma_f32 v[102:103], v[68:69], s[12:13], v[102:103] op_sel_hi:[1,0,1]
	s_cmp_le_i32 s0, s27
	v_pk_fma_f32 v[80:81], v[66:67], s[12:13], v[202:203] op_sel_hi:[1,0,1] neg_lo:[0,0,1] neg_hi:[0,0,1]
	s_cbranch_scc1 .LBB0_655
	v_cmp_gt_i32_e64 s[92:93], 26, v199
	v_cmp_gt_i32_e64 s[94:95], 27, v199
	v_cmp_gt_i32_e64 s[90:91], 25, v199
	s_and_b64 s[92:93], s[94:95], s[92:93]
	v_cmp_gt_i32_e64 s[88:89], 24, v199
	s_and_b64 s[90:91], s[92:93], s[90:91]
	v_cmp_gt_i32_e64 s[86:87], 19, v199
	s_and_b64 s[88:89], s[90:91], s[88:89]
	v_cmp_gt_i32_e64 s[84:85], 18, v199
	s_and_b64 s[86:87], s[88:89], s[86:87]
	v_cmp_gt_i32_e64 s[82:83], 17, v199
	s_and_b64 s[84:85], s[86:87], s[84:85]
	v_cmp_gt_i32_e64 s[80:81], 16, v199
	s_and_b64 s[82:83], s[84:85], s[82:83]
	v_cmp_gt_i32_e64 s[78:79], 11, v199
	s_and_b64 s[80:81], s[82:83], s[80:81]
	v_cmp_gt_i32_e64 s[76:77], 10, v199
	s_and_b64 s[78:79], s[80:81], s[78:79]
	v_cmp_gt_i32_e64 s[74:75], 9, v199
	s_and_b64 s[76:77], s[78:79], s[76:77]
	v_cmp_gt_i32_e64 s[72:73], 8, v199
	s_and_b64 s[74:75], s[76:77], s[74:75]
	v_cmp_gt_i32_e64 s[70:71], 3, v199
	s_and_b64 s[72:73], s[74:75], s[72:73]
	v_cmp_gt_i32_e64 s[68:69], 2, v199
	s_and_b64 s[70:71], s[72:73], s[70:71]
	v_cmp_gt_i32_e64 s[2:3], 1, v199
	s_and_b64 s[68:69], s[70:71], s[68:69]
	v_cmp_gt_i32_e64 s[0:1], 0, v199
	s_and_b64 s[2:3], s[68:69], s[2:3]
	s_and_b64 s[0:1], s[2:3], s[0:1]
	v_cmp_gt_i32_e64 s[66:67], 58, v199
	v_cndmask_b32_e64 v96, v96, v175, s[0:1]
	v_cmp_gt_i32_e64 s[0:1], 59, v199
	v_cmp_gt_i32_e64 s[64:65], 57, v199
	v_cmp_gt_i32_e64 s[62:63], 56, v199
	v_cndmask_b32_e64 v71, v71, v175, s[0:1]
	s_and_b64 s[0:1], s[0:1], s[66:67]
	v_cndmask_b32_e64 v70, v70, v175, s[0:1]
	s_and_b64 s[0:1], s[0:1], s[64:65]
	v_cmp_gt_i32_e64 s[60:61], 51, v199
	v_cndmask_b32_e64 v83, v83, v175, s[0:1]
	s_and_b64 s[0:1], s[0:1], s[62:63]
	v_cmp_gt_i32_e64 s[58:59], 50, v199
	v_cndmask_b32_e64 v82, v82, v175, s[0:1]
	s_and_b64 s[0:1], s[0:1], s[60:61]
	v_cmp_gt_i32_e64 s[56:57], 49, v199
	v_cndmask_b32_e64 v77, v77, v175, s[0:1]
	s_and_b64 s[0:1], s[0:1], s[58:59]
	v_cmp_gt_i32_e64 s[54:55], 48, v199
	v_cndmask_b32_e64 v76, v76, v175, s[0:1]
	s_and_b64 s[0:1], s[0:1], s[56:57]
	v_cmp_gt_i32_e64 s[52:53], 43, v199
	v_cndmask_b32_e64 v75, v75, v175, s[0:1]
	s_and_b64 s[0:1], s[0:1], s[54:55]
	v_cmp_gt_i32_e64 s[50:51], 42, v199
	v_cndmask_b32_e64 v74, v74, v175, s[0:1]
	s_and_b64 s[0:1], s[0:1], s[52:53]
	v_cmp_gt_i32_e64 s[48:49], 41, v199
	v_cndmask_b32_e64 v101, v101, v175, s[0:1]
	s_and_b64 s[0:1], s[0:1], s[50:51]
	v_cmp_gt_i32_e64 s[46:47], 40, v199
	v_cndmask_b32_e64 v100, v100, v175, s[0:1]
	s_and_b64 s[0:1], s[0:1], s[48:49]
	v_cmp_gt_i32_e64 s[44:45], 35, v199
	v_cndmask_b32_e64 v79, v79, v175, s[0:1]
	s_and_b64 s[0:1], s[0:1], s[46:47]
	v_cmp_gt_i32_e64 s[42:43], 34, v199
	v_cndmask_b32_e64 v78, v78, v175, s[0:1]
	s_and_b64 s[0:1], s[0:1], s[44:45]
	v_cmp_gt_i32_e64 s[40:41], 33, v199
	v_cndmask_b32_e64 v103, v103, v175, s[0:1]
	s_and_b64 s[0:1], s[0:1], s[42:43]
	v_cmp_gt_i32_e32 vcc, 32, v199
	v_cndmask_b32_e64 v102, v102, v175, s[0:1]
	s_and_b64 s[0:1], s[0:1], s[40:41]
	v_cndmask_b32_e64 v94, v94, v175, s[88:89]
	v_readlane_b32 s88, v242, 2
	s_and_b64 vcc, s[0:1], vcc
	v_cndmask_b32_e64 v87, v87, v175, s[94:95]
	v_cndmask_b32_e64 v86, v86, v175, s[92:93]
	s_movk_i32 s93, 0x6018
	s_mov_b32 s92, 0xf800000
	v_cndmask_b32_e64 v95, v95, v175, s[90:91]
	s_mov_b64 s[90:91], s[16:17]
	v_readlane_b32 s89, v242, 3
	v_cndmask_b32_e64 v93, v93, v175, s[86:87]
	v_readlane_b32 s86, v242, 0
	v_cndmask_b32_e64 v92, v92, v175, s[84:85]
	v_cndmask_b32_e64 v91, v91, v175, s[82:83]
	s_movk_i32 s83, 0x6000
	v_cndmask_b32_e64 v90, v90, v175, s[80:81]
	v_cndmask_b32_e64 v89, v89, v175, s[78:79]
	v_cndmask_b32_e64 v88, v88, v175, s[76:77]
	v_cndmask_b32_e64 v99, v99, v175, s[74:75]
	v_cndmask_b32_e64 v98, v98, v175, s[72:73]
	v_cndmask_b32_e64 v85, v85, v175, s[70:71]
	v_cndmask_b32_e64 v84, v84, v175, s[68:69]
	v_cndmask_b32_e64 v97, v97, v175, s[2:3]
	s_mov_b32 s56, s30
	v_cndmask_b32_e64 v81, v81, v175, s[0:1]
	v_cndmask_b32_e32 v80, v80, v175, vcc
	v_readlane_b32 s87, v242, 1

.LBB0_823:
	v_add_u32_e32 v182, s9, v158
	v_add_u32_e32 v66, 1, v182
	v_mad_i64_i32 v[66:67], s[0:1], v66, s33, v[130:131]
	v_add_u32_e32 v68, 33, v182
	v_mad_i64_i32 v[68:69], s[0:1], v68, s33, v[130:131]
	global_load_dwordx4 v[114:117], v[66:67], off offset:2048
	global_load_dwordx4 v[122:125], v[66:67], off offset:1024
	global_load_dwordx4 v[118:121], v[68:69], off offset:2048
	global_load_dwordx4 v[126:129], v[68:69], off offset:1024
	ds_read_b128 v[228:231], v159 offset:49152
	ds_read_b128 v[232:235], v160 offset:49152
	ds_read_b128 v[236:239], v159 offset:57344
	ds_read_b128 v[248:251], v160 offset:57344
	ds_read_b128 v[252:255], v161 offset:49152
	s_waitcnt lgkmcnt(4)
	v_mfma_f32_32x32x16_bf16 v[82:97], v[228:231], v[110:113], 0
	ds_read_b128 v[228:231], v161 offset:57344
	v_exp_f32_e32 v206, v132
	v_add_f32_e32 v132, 0, v197
	v_add_f32_e32 v132, v199, v132
	v_add_f32_e32 v132, v195, v132
	v_add_f32_e32 v132, v198, v132
	v_add_f32_e32 v132, v193, v132
	v_add_f32_e32 v132, v196, v132
	v_add_f32_e32 v132, v192, v132
	v_add_f32_e32 v132, v194, v132
	v_add_f32_e32 v132, v189, v132
	s_waitcnt lgkmcnt(4)
	v_mfma_f32_32x32x16_bf16 v[82:97], v[232:235], v[106:109], v[82:97]
	ds_read_b128 v[232:235], v162 offset:49152
	v_add_f32_e32 v132, v191, v132
	v_add_f32_e32 v132, v187, v132
	v_add_f32_e32 v132, v190, v132
	v_exp_f32_e32 v146, v146
	v_add_f32_e32 v132, v185, v132
	v_exp_f32_e32 v147, v147
	v_add_f32_e32 v132, v188, v132
	v_exp_f32_e32 v144, v144
	v_add_f32_e32 v132, v184, v132
	v_exp_f32_e32 v145, v145
	s_waitcnt lgkmcnt(4)
	v_mfma_f32_32x32x16_bf16 v[66:81], v[236:239], v[110:113], 0
	ds_read_b128 v[236:239], v162 offset:57344
	v_add_f32_e32 v132, v186, v132
	v_exp_f32_e32 v142, v142
	v_add_f32_e32 v132, v146, v132
	v_exp_f32_e32 v143, v143
	v_add_f32_e32 v132, v147, v132
	v_exp_f32_e32 v181, v140
	v_add_f32_e32 v132, v144, v132
	v_exp_f32_e32 v183, v141
	v_add_f32_e32 v132, v145, v132
	v_exp_f32_e32 v200, v138
	s_waitcnt lgkmcnt(4)
	v_mfma_f32_32x32x16_bf16 v[66:81], v[248:251], v[106:109], v[66:81]
	v_add_f32_e32 v132, v142, v132
	v_exp_f32_e32 v201, v139
	v_add_f32_e32 v132, v143, v132
	v_exp_f32_e32 v202, v136
	v_add_f32_e32 v132, v181, v132
	v_exp_f32_e32 v203, v137
	v_add_f32_e32 v132, v183, v132
	v_exp_f32_e32 v204, v134
	v_add_f32_e32 v132, v200, v132
	v_exp_f32_e32 v205, v135
	s_waitcnt lgkmcnt(3)
	v_mfma_f32_32x32x16_bf16 v[82:97], v[252:255], v[102:105], v[82:97]
	v_add_f32_e32 v132, v201, v132
	v_add_f32_e32 v132, v202, v132
	v_exp_f32_e32 v207, v133
	v_add_f32_e32 v132, v203, v132
	v_add_f32_e32 v132, v204, v132
	v_add_f32_e32 v132, v205, v132
	v_add_f32_e32 v132, v206, v132
	v_add_f32_e32 v179, v207, v132
	v_mov_b32_e32 v180, v179
	s_nop 1
	s_waitcnt lgkmcnt(2)
	v_mfma_f32_32x32x16_bf16 v[66:81], v[228:231], v[102:105], v[66:81]
	v_permlane32_swap_b32_e32 v179, v180
	v_cvt_pk_bf16_f32 v132, v197, v199
	v_cvt_pk_bf16_f32 v133, v195, v198
	v_cvt_pk_bf16_f32 v134, v193, v196
	v_cvt_pk_bf16_f32 v135, v192, v194
	v_cvt_pk_bf16_f32 v136, v189, v191
	v_cvt_pk_bf16_f32 v137, v187, v190
	v_cvt_pk_bf16_f32 v138, v185, v188
	v_cvt_pk_bf16_f32 v139, v184, v186
	v_cvt_pk_bf16_f32 v140, v146, v147
	s_waitcnt lgkmcnt(1)
	v_mfma_f32_32x32x16_bf16 v[82:97], v[232:235], v[98:101], v[82:97]
	v_cvt_pk_bf16_f32 v141, v144, v145
	v_cvt_pk_bf16_f32 v142, v142, v143
	v_cvt_pk_bf16_f32 v143, v181, v183
	v_cvt_pk_bf16_f32 v144, v200, v201
	v_cvt_pk_bf16_f32 v145, v202, v203
	v_cvt_pk_bf16_f32 v146, v204, v205
	v_cvt_pk_bf16_f32 v147, v206, v207
	s_nop 0
	v_permlane32_swap_b32_e32 v132, v134
	v_permlane32_swap_b32_e32 v133, v135
	s_waitcnt lgkmcnt(0)
	v_mfma_f32_32x32x16_bf16 v[66:81], v[236:239], v[98:101], v[66:81]
	v_permlane32_swap_b32_e32 v136, v138
	v_permlane32_swap_b32_e32 v137, v139
	v_permlane32_swap_b32_e32 v140, v142
	v_permlane32_swap_b32_e32 v141, v143
	v_permlane32_swap_b32_e32 v144, v146
	v_permlane32_swap_b32_e32 v145, v147
	ds_read_b64_tr_b16 v[184:185], v153 offset:0
	ds_read_b64_tr_b16 v[186:187], v153 offset:0x800
	ds_read_b64_tr_b16 v[188:189], v153 offset:0x1000
	ds_read_b64_tr_b16 v[190:191], v153 offset:0x1800
	ds_read_b64_tr_b16 v[192:193], v153 offset:0x2000
	ds_read_b64_tr_b16 v[194:195], v153 offset:0x2800
	ds_read_b64_tr_b16 v[196:197], v153 offset:0x3000
	ds_read_b64_tr_b16 v[198:199], v153 offset:0x3800
	s_nop 0
	s_waitcnt lgkmcnt(6)
	v_mfma_f32_32x32x16_bf16 v[50:65], v[132:135], v[184:187], v[50:65]
	ds_read_b64_tr_b16 v[184:185], v153 offset:0x200
	ds_read_b64_tr_b16 v[186:187], v153 offset:0xa00
	s_waitcnt lgkmcnt(6)
	v_mfma_f32_32x32x16_bf16 v[50:65], v[136:139], v[188:191], v[50:65]
	ds_read_b64_tr_b16 v[188:189], v153 offset:0x1200
	ds_read_b64_tr_b16 v[190:191], v153 offset:0x1a00
	s_waitcnt lgkmcnt(6)
	v_mfma_f32_32x32x16_bf16 v[50:65], v[140:143], v[192:195], v[50:65]
	ds_read_b64_tr_b16 v[192:193], v153 offset:0x2200
	ds_read_b64_tr_b16 v[194:195], v153 offset:0x2a00
	s_waitcnt lgkmcnt(6)
	v_mfma_f32_32x32x16_bf16 v[50:65], v[144:147], v[196:199], v[50:65]
	ds_read_b64_tr_b16 v[196:197], v153 offset:0x3200
	ds_read_b64_tr_b16 v[198:199], v153 offset:0x3a00
	s_waitcnt lgkmcnt(6)
	v_mfma_f32_32x32x16_bf16 v[34:49], v[132:135], v[184:187], v[34:49]
	ds_read_b64_tr_b16 v[184:185], v153 offset:0x400
	ds_read_b64_tr_b16 v[186:187], v153 offset:0xc00
	s_waitcnt lgkmcnt(6)
	v_mfma_f32_32x32x16_bf16 v[34:49], v[136:139], v[188:191], v[34:49]
	ds_read_b64_tr_b16 v[188:189], v153 offset:0x1400
	ds_read_b64_tr_b16 v[190:191], v153 offset:0x1c00
	s_waitcnt lgkmcnt(6)
	v_mfma_f32_32x32x16_bf16 v[34:49], v[140:143], v[192:195], v[34:49]
	ds_read_b64_tr_b16 v[192:193], v153 offset:0x2400
	ds_read_b64_tr_b16 v[194:195], v153 offset:0x2c00
	s_waitcnt lgkmcnt(6)
	v_mfma_f32_32x32x16_bf16 v[34:49], v[144:147], v[196:199], v[34:49]
	ds_read_b64_tr_b16 v[196:197], v153 offset:0x3400
	ds_read_b64_tr_b16 v[198:199], v153 offset:0x3c00
	s_waitcnt lgkmcnt(6)
	v_mfma_f32_32x32x16_bf16 v[18:33], v[132:135], v[184:187], v[18:33]
	ds_read_b64_tr_b16 v[184:185], v153 offset:0x600
	ds_read_b64_tr_b16 v[186:187], v153 offset:0xe00
	s_waitcnt lgkmcnt(6)
	v_mfma_f32_32x32x16_bf16 v[18:33], v[136:139], v[188:191], v[18:33]
	ds_read_b64_tr_b16 v[188:189], v153 offset:0x1600
	ds_read_b64_tr_b16 v[190:191], v153 offset:0x1e00
	s_waitcnt lgkmcnt(6)
	v_mfma_f32_32x32x16_bf16 v[18:33], v[140:143], v[192:195], v[18:33]
	ds_read_b64_tr_b16 v[192:193], v153 offset:0x2600
	ds_read_b64_tr_b16 v[194:195], v153 offset:0x2e00
	s_waitcnt lgkmcnt(6)
	v_mfma_f32_32x32x16_bf16 v[18:33], v[144:147], v[196:199], v[18:33]
	ds_read_b64_tr_b16 v[196:197], v153 offset:0x3600
	ds_read_b64_tr_b16 v[198:199], v153 offset:0x3e00
	s_waitcnt lgkmcnt(6)
	v_mfma_f32_32x32x16_bf16 v[2:17], v[132:135], v[184:187], v[2:17]
	s_waitcnt lgkmcnt(4)
	v_mfma_f32_32x32x16_bf16 v[2:17], v[136:139], v[188:191], v[2:17]
	s_waitcnt lgkmcnt(2)
	v_mfma_f32_32x32x16_bf16 v[2:17], v[140:143], v[192:195], v[2:17]
	s_waitcnt lgkmcnt(0)
	v_mfma_f32_32x32x16_bf16 v[2:17], v[144:147], v[196:199], v[2:17]
	s_cmp_le_i32 s9, s25
	s_cbranch_scc1 .LBB0_825
	v_add_u32_e32 v132, 64, v169
	v_cmp_gt_i32_e64 s[92:93], 26, v132
	v_cmp_gt_i32_e64 s[94:95], 27, v132
	v_cmp_gt_i32_e64 s[90:91], 25, v132
	s_and_b64 s[92:93], s[94:95], s[92:93]
	v_cmp_gt_i32_e64 s[88:89], 24, v132
	s_and_b64 s[90:91], s[92:93], s[90:91]
	v_cmp_gt_i32_e64 s[86:87], 19, v132
	s_and_b64 s[88:89], s[90:91], s[88:89]
	v_cmp_gt_i32_e64 s[84:85], 18, v132
	s_and_b64 s[86:87], s[88:89], s[86:87]
	v_cmp_gt_i32_e64 s[82:83], 17, v132
	s_and_b64 s[84:85], s[86:87], s[84:85]
	v_cmp_gt_i32_e64 s[80:81], 16, v132
	s_and_b64 s[82:83], s[84:85], s[82:83]
	v_cmp_gt_i32_e64 s[78:79], 11, v132
	s_and_b64 s[80:81], s[82:83], s[80:81]
	v_cmp_gt_i32_e64 s[76:77], 10, v132
	s_and_b64 s[78:79], s[80:81], s[78:79]
	v_cmp_gt_i32_e64 s[74:75], 9, v132
	s_and_b64 s[76:77], s[78:79], s[76:77]
	v_cmp_gt_i32_e64 s[72:73], 8, v132
	s_and_b64 s[74:75], s[76:77], s[74:75]
	v_cmp_gt_i32_e64 s[70:71], 3, v132
	s_and_b64 s[72:73], s[74:75], s[72:73]
	v_cmp_gt_i32_e64 s[68:69], 2, v132
	s_and_b64 s[70:71], s[72:73], s[70:71]
	v_cmp_gt_i32_e64 s[2:3], 1, v132
	s_and_b64 s[68:69], s[70:71], s[68:69]
	v_cmp_gt_i32_e64 s[0:1], 0, v132
	s_and_b64 s[2:3], s[68:69], s[2:3]
	s_and_b64 s[0:1], s[2:3], s[0:1]
	v_cmp_gt_i32_e64 s[66:67], 58, v132
	v_cndmask_b32_e64 v82, v82, v175, s[0:1]
	v_cmp_gt_i32_e64 s[0:1], 59, v132
	v_cmp_gt_i32_e64 s[64:65], 57, v132
	v_cmp_gt_i32_e64 s[62:63], 56, v132
	v_cndmask_b32_e64 v81, v81, v175, s[0:1]
	s_and_b64 s[0:1], s[0:1], s[66:67]
	v_cndmask_b32_e64 v80, v80, v175, s[0:1]
	s_and_b64 s[0:1], s[0:1], s[64:65]
	v_cmp_gt_i32_e64 s[60:61], 51, v132
	v_cndmask_b32_e64 v79, v79, v175, s[0:1]
	s_and_b64 s[0:1], s[0:1], s[62:63]
	v_cmp_gt_i32_e64 s[58:59], 50, v132
	v_cndmask_b32_e64 v78, v78, v175, s[0:1]
	s_and_b64 s[0:1], s[0:1], s[60:61]
	v_cmp_gt_i32_e64 s[56:57], 49, v132
	v_cndmask_b32_e64 v77, v77, v175, s[0:1]
	s_and_b64 s[0:1], s[0:1], s[58:59]
	v_cmp_gt_i32_e64 s[54:55], 48, v132
	v_cndmask_b32_e64 v76, v76, v175, s[0:1]
	s_and_b64 s[0:1], s[0:1], s[56:57]
	v_cmp_gt_i32_e64 s[52:53], 43, v132
	v_cndmask_b32_e64 v75, v75, v175, s[0:1]
	s_and_b64 s[0:1], s[0:1], s[54:55]
	v_cmp_gt_i32_e64 s[50:51], 42, v132
	v_cndmask_b32_e64 v74, v74, v175, s[0:1]
	s_and_b64 s[0:1], s[0:1], s[52:53]
	v_cmp_gt_i32_e64 s[48:49], 41, v132
	v_cndmask_b32_e64 v73, v73, v175, s[0:1]
	s_and_b64 s[0:1], s[0:1], s[50:51]
	v_cmp_gt_i32_e64 s[46:47], 40, v132
	v_cndmask_b32_e64 v72, v72, v175, s[0:1]
	s_and_b64 s[0:1], s[0:1], s[48:49]
	v_cmp_gt_i32_e64 s[44:45], 35, v132
	v_cndmask_b32_e64 v71, v71, v175, s[0:1]
	s_and_b64 s[0:1], s[0:1], s[46:47]
	v_cmp_gt_i32_e64 s[42:43], 34, v132
	v_cndmask_b32_e64 v70, v70, v175, s[0:1]
	s_and_b64 s[0:1], s[0:1], s[44:45]
	v_cmp_gt_i32_e64 s[40:41], 33, v132
	v_cndmask_b32_e64 v69, v69, v175, s[0:1]
	s_and_b64 s[0:1], s[0:1], s[42:43]
	v_cmp_gt_i32_e32 vcc, 32, v132
	v_cndmask_b32_e64 v68, v68, v175, s[0:1]
	s_and_b64 s[0:1], s[0:1], s[40:41]
	s_and_b64 vcc, s[0:1], vcc
	v_cndmask_b32_e64 v97, v97, v175, s[94:95]
	v_cndmask_b32_e64 v96, v96, v175, s[92:93]
	v_cndmask_b32_e64 v95, v95, v175, s[90:91]
	v_cndmask_b32_e64 v94, v94, v175, s[88:89]
	v_cndmask_b32_e64 v93, v93, v175, s[86:87]
	v_cndmask_b32_e64 v92, v92, v175, s[84:85]
	v_cndmask_b32_e64 v91, v91, v175, s[82:83]
	v_cndmask_b32_e64 v90, v90, v175, s[80:81]
	v_cndmask_b32_e64 v89, v89, v175, s[78:79]
	v_cndmask_b32_e64 v88, v88, v175, s[76:77]
	v_cndmask_b32_e64 v87, v87, v175, s[74:75]
	v_cndmask_b32_e64 v86, v86, v175, s[72:73]
	v_cndmask_b32_e64 v85, v85, v175, s[70:71]
	v_cndmask_b32_e64 v84, v84, v175, s[68:69]
	v_cndmask_b32_e64 v83, v83, v175, s[2:3]
	v_cndmask_b32_e64 v67, v67, v175, s[0:1]
	v_cndmask_b32_e32 v66, v66, v175, vcc

.LBB0_831:
	ds_read_b128 v[228:231], v159 offset:32768
	ds_read_b128 v[232:235], v160 offset:32768
	ds_read_b128 v[236:239], v159 offset:40960
	ds_read_b128 v[248:251], v160 offset:40960
	ds_read_b128 v[252:255], v161 offset:32768
	s_waitcnt lgkmcnt(4)
	v_mfma_f32_32x32x16_bf16 v[82:97], v[228:231], v[110:113], 0
	ds_read_b128 v[228:231], v161 offset:40960
	v_add_f32_e32 v182, 0, v146
	v_add_f32_e32 v182, v168, v182
	v_add_f32_e32 v182, v144, v182
	v_add_f32_e32 v182, v147, v182
	v_add_f32_e32 v182, v142, v182
	v_add_f32_e32 v182, v145, v182
	v_add_f32_e32 v182, v141, v182
	v_add_f32_e32 v182, v143, v182
	v_add_f32_e32 v182, v138, v182
	v_add_f32_e32 v182, v140, v182
	s_waitcnt lgkmcnt(4)
	v_mfma_f32_32x32x16_bf16 v[82:97], v[232:235], v[106:109], v[82:97]
	ds_read_b128 v[232:235], v162 offset:32768
	v_add_f32_e32 v182, v136, v182
	v_add_f32_e32 v182, v139, v182
	v_exp_f32_e32 v199, v184
	v_add_f32_e32 v182, v134, v182
	v_exp_f32_e32 v200, v185
	v_add_f32_e32 v182, v137, v182
	v_exp_f32_e32 v201, v186
	v_add_f32_e32 v182, v133, v182
	v_exp_f32_e32 v202, v187
	v_add_f32_e32 v182, v135, v182
	s_waitcnt lgkmcnt(4)
	v_mfma_f32_32x32x16_bf16 v[66:81], v[236:239], v[110:113], 0
	ds_read_b128 v[236:239], v162 offset:40960
	v_exp_f32_e32 v188, v188
	v_add_f32_e32 v182, v199, v182
	v_exp_f32_e32 v189, v189
	v_add_f32_e32 v182, v200, v182
	v_exp_f32_e32 v190, v190
	v_add_f32_e32 v182, v201, v182
	v_exp_f32_e32 v191, v191
	v_add_f32_e32 v182, v202, v182
	v_exp_f32_e32 v192, v192
	v_add_f32_e32 v182, v188, v182
	s_waitcnt lgkmcnt(4)
	v_mfma_f32_32x32x16_bf16 v[66:81], v[248:251], v[106:109], v[66:81]
	v_exp_f32_e32 v193, v193
	v_add_f32_e32 v182, v189, v182
	v_exp_f32_e32 v194, v194
	v_add_f32_e32 v182, v190, v182
	v_exp_f32_e32 v195, v195
	v_add_f32_e32 v182, v191, v182
	v_exp_f32_e32 v196, v196
	v_add_f32_e32 v182, v192, v182
	v_exp_f32_e32 v197, v197
	v_add_f32_e32 v182, v193, v182
	s_waitcnt lgkmcnt(3)
	v_mfma_f32_32x32x16_bf16 v[82:97], v[252:255], v[102:105], v[82:97]
	v_exp_f32_e32 v198, v198
	v_add_f32_e32 v182, v194, v182
	v_exp_f32_e32 v203, v183
	v_add_f32_e32 v182, v195, v182
	v_add_f32_e32 v182, v196, v182
	v_add_f32_e32 v182, v197, v182
	v_add_f32_e32 v182, v198, v182
	v_add_f32_e32 v182, v203, v182
	v_mov_b32_e32 v183, v182
	s_nop 1
	s_waitcnt lgkmcnt(2)
	v_mfma_f32_32x32x16_bf16 v[66:81], v[228:231], v[102:105], v[66:81]
	v_permlane32_swap_b32_e32 v182, v183
	v_cvt_pk_bf16_f32 v184, v146, v168
	v_cvt_pk_bf16_f32 v185, v144, v147
	v_cvt_pk_bf16_f32 v186, v142, v145
	v_cvt_pk_bf16_f32 v187, v141, v143
	v_cvt_pk_bf16_f32 v138, v138, v140
	v_cvt_pk_bf16_f32 v139, v136, v139
	v_cvt_pk_bf16_f32 v140, v134, v137
	v_cvt_pk_bf16_f32 v141, v133, v135
	v_cvt_pk_bf16_f32 v134, v199, v200
	s_waitcnt lgkmcnt(1)
	v_mfma_f32_32x32x16_bf16 v[82:97], v[232:235], v[98:101], v[82:97]
	v_cvt_pk_bf16_f32 v135, v201, v202
	v_cvt_pk_bf16_f32 v136, v188, v189
	v_cvt_pk_bf16_f32 v137, v190, v191
	v_cvt_pk_bf16_f32 v142, v192, v193
	v_cvt_pk_bf16_f32 v143, v194, v195
	v_cvt_pk_bf16_f32 v144, v196, v197
	v_cvt_pk_bf16_f32 v145, v198, v203
	s_nop 0
	v_permlane32_swap_b32_e32 v184, v186
	v_permlane32_swap_b32_e32 v185, v187
	s_waitcnt lgkmcnt(0)
	v_mfma_f32_32x32x16_bf16 v[66:81], v[236:239], v[98:101], v[66:81]
	v_permlane32_swap_b32_e32 v138, v140
	v_permlane32_swap_b32_e32 v139, v141
	v_permlane32_swap_b32_e32 v134, v136
	v_permlane32_swap_b32_e32 v135, v137
	v_permlane32_swap_b32_e32 v142, v144
	v_permlane32_swap_b32_e32 v143, v145
	ds_read_b64_tr_b16 v[188:189], v153 offset:0x4000
	ds_read_b64_tr_b16 v[190:191], v153 offset:0x4800
	ds_read_b64_tr_b16 v[192:193], v153 offset:0x5000
	ds_read_b64_tr_b16 v[194:195], v153 offset:0x5800
	ds_read_b64_tr_b16 v[196:197], v153 offset:0x6000
	ds_read_b64_tr_b16 v[198:199], v153 offset:0x6800
	ds_read_b64_tr_b16 v[200:201], v153 offset:0x7000
	ds_read_b64_tr_b16 v[202:203], v153 offset:0x7800
	s_nop 0
	s_waitcnt lgkmcnt(6)
	v_mfma_f32_32x32x16_bf16 v[50:65], v[184:187], v[188:191], v[50:65]
	ds_read_b64_tr_b16 v[188:189], v153 offset:0x4200
	ds_read_b64_tr_b16 v[190:191], v153 offset:0x4a00
	s_waitcnt lgkmcnt(6)
	v_mfma_f32_32x32x16_bf16 v[50:65], v[138:141], v[192:195], v[50:65]
	ds_read_b64_tr_b16 v[192:193], v153 offset:0x5200
	ds_read_b64_tr_b16 v[194:195], v153 offset:0x5a00
	s_waitcnt lgkmcnt(6)
	v_mfma_f32_32x32x16_bf16 v[50:65], v[134:137], v[196:199], v[50:65]
	ds_read_b64_tr_b16 v[196:197], v153 offset:0x6200
	ds_read_b64_tr_b16 v[198:199], v153 offset:0x6a00
	s_waitcnt lgkmcnt(6)
	v_mfma_f32_32x32x16_bf16 v[50:65], v[142:145], v[200:203], v[50:65]
	ds_read_b64_tr_b16 v[200:201], v153 offset:0x7200
	ds_read_b64_tr_b16 v[202:203], v153 offset:0x7a00
	s_waitcnt lgkmcnt(6)
	v_mfma_f32_32x32x16_bf16 v[34:49], v[184:187], v[188:191], v[34:49]
	ds_read_b64_tr_b16 v[188:189], v153 offset:0x4400
	ds_read_b64_tr_b16 v[190:191], v153 offset:0x4c00
	s_waitcnt lgkmcnt(6)
	v_mfma_f32_32x32x16_bf16 v[34:49], v[138:141], v[192:195], v[34:49]
	ds_read_b64_tr_b16 v[192:193], v153 offset:0x5400
	ds_read_b64_tr_b16 v[194:195], v153 offset:0x5c00
	s_waitcnt lgkmcnt(6)
	v_mfma_f32_32x32x16_bf16 v[34:49], v[134:137], v[196:199], v[34:49]
	ds_read_b64_tr_b16 v[196:197], v153 offset:0x6400
	ds_read_b64_tr_b16 v[198:199], v153 offset:0x6c00
	s_waitcnt lgkmcnt(6)
	v_mfma_f32_32x32x16_bf16 v[34:49], v[142:145], v[200:203], v[34:49]
	ds_read_b64_tr_b16 v[200:201], v153 offset:0x7400
	ds_read_b64_tr_b16 v[202:203], v153 offset:0x7c00
	s_waitcnt lgkmcnt(6)
	v_mfma_f32_32x32x16_bf16 v[18:33], v[184:187], v[188:191], v[18:33]
	ds_read_b64_tr_b16 v[188:189], v153 offset:0x4600
	ds_read_b64_tr_b16 v[190:191], v153 offset:0x4e00
	s_waitcnt lgkmcnt(6)
	v_mfma_f32_32x32x16_bf16 v[18:33], v[138:141], v[192:195], v[18:33]
	ds_read_b64_tr_b16 v[192:193], v153 offset:0x5600
	ds_read_b64_tr_b16 v[194:195], v153 offset:0x5e00
	s_waitcnt lgkmcnt(6)
	v_mfma_f32_32x32x16_bf16 v[18:33], v[134:137], v[196:199], v[18:33]
	ds_read_b64_tr_b16 v[196:197], v153 offset:0x6600
	ds_read_b64_tr_b16 v[198:199], v153 offset:0x6e00
	s_waitcnt lgkmcnt(6)
	v_mfma_f32_32x32x16_bf16 v[18:33], v[142:145], v[200:203], v[18:33]
	ds_read_b64_tr_b16 v[200:201], v153 offset:0x7600
	ds_read_b64_tr_b16 v[202:203], v153 offset:0x7e00
	s_waitcnt lgkmcnt(6)
	v_mfma_f32_32x32x16_bf16 v[2:17], v[184:187], v[188:191], v[2:17]
	s_waitcnt lgkmcnt(4)
	v_mfma_f32_32x32x16_bf16 v[2:17], v[138:141], v[192:195], v[2:17]
	s_waitcnt lgkmcnt(2)
	v_mfma_f32_32x32x16_bf16 v[2:17], v[134:137], v[196:199], v[2:17]
	s_waitcnt lgkmcnt(0)
	v_mfma_f32_32x32x16_bf16 v[2:17], v[142:145], v[200:203], v[2:17]
	s_add_i32 s0, s9, 64
	s_cmp_le_i32 s0, s25
	s_cbranch_scc1 .LBB0_833
	v_cmp_gt_i32_e64 s[92:93], 26, v169
	v_cmp_gt_i32_e64 s[94:95], 27, v169
	v_cmp_gt_i32_e64 s[90:91], 25, v169
	s_and_b64 s[92:93], s[94:95], s[92:93]
	v_cmp_gt_i32_e64 s[88:89], 24, v169
	s_and_b64 s[90:91], s[92:93], s[90:91]
	v_cmp_gt_i32_e64 s[86:87], 19, v169
	s_and_b64 s[88:89], s[90:91], s[88:89]
	v_cmp_gt_i32_e64 s[84:85], 18, v169
	s_and_b64 s[86:87], s[88:89], s[86:87]
	v_cmp_gt_i32_e64 s[82:83], 17, v169
	s_and_b64 s[84:85], s[86:87], s[84:85]
	v_cmp_gt_i32_e64 s[80:81], 16, v169
	s_and_b64 s[82:83], s[84:85], s[82:83]
	v_cmp_gt_i32_e64 s[78:79], 11, v169
	s_and_b64 s[80:81], s[82:83], s[80:81]
	v_cmp_gt_i32_e64 s[76:77], 10, v169
	s_and_b64 s[78:79], s[80:81], s[78:79]
	v_cmp_gt_i32_e64 s[74:75], 9, v169
	s_and_b64 s[76:77], s[78:79], s[76:77]
	v_cmp_gt_i32_e64 s[72:73], 8, v169
	s_and_b64 s[74:75], s[76:77], s[74:75]
	v_cmp_gt_i32_e64 s[70:71], 3, v169
	s_and_b64 s[72:73], s[74:75], s[72:73]
	v_cmp_gt_i32_e64 s[68:69], 2, v169
	s_and_b64 s[70:71], s[72:73], s[70:71]
	v_cmp_gt_i32_e64 s[2:3], 1, v169
	s_and_b64 s[68:69], s[70:71], s[68:69]
	v_cmp_gt_i32_e64 s[0:1], 0, v169
	s_and_b64 s[2:3], s[68:69], s[2:3]
	s_and_b64 s[0:1], s[2:3], s[0:1]
	v_cmp_gt_i32_e64 s[66:67], 58, v169
	v_cndmask_b32_e64 v82, v82, v175, s[0:1]
	v_cmp_gt_i32_e64 s[0:1], 59, v169
	v_cmp_gt_i32_e64 s[64:65], 57, v169
	v_cmp_gt_i32_e64 s[62:63], 56, v169
	v_cndmask_b32_e64 v81, v81, v175, s[0:1]
	s_and_b64 s[0:1], s[0:1], s[66:67]
	v_cndmask_b32_e64 v80, v80, v175, s[0:1]
	s_and_b64 s[0:1], s[0:1], s[64:65]
	v_cmp_gt_i32_e64 s[60:61], 51, v169
	v_cndmask_b32_e64 v79, v79, v175, s[0:1]
	s_and_b64 s[0:1], s[0:1], s[62:63]
	v_cmp_gt_i32_e64 s[58:59], 50, v169
	v_cndmask_b32_e64 v78, v78, v175, s[0:1]
	s_and_b64 s[0:1], s[0:1], s[60:61]
	v_cmp_gt_i32_e64 s[56:57], 49, v169
	v_cndmask_b32_e64 v77, v77, v175, s[0:1]
	s_and_b64 s[0:1], s[0:1], s[58:59]
	v_cmp_gt_i32_e64 s[54:55], 48, v169
	v_cndmask_b32_e64 v76, v76, v175, s[0:1]
	s_and_b64 s[0:1], s[0:1], s[56:57]
	v_cmp_gt_i32_e64 s[52:53], 43, v169
	v_cndmask_b32_e64 v75, v75, v175, s[0:1]
	s_and_b64 s[0:1], s[0:1], s[54:55]
	v_cmp_gt_i32_e64 s[50:51], 42, v169
	v_cndmask_b32_e64 v74, v74, v175, s[0:1]
	s_and_b64 s[0:1], s[0:1], s[52:53]
	v_cmp_gt_i32_e64 s[48:49], 41, v169
	v_cndmask_b32_e64 v73, v73, v175, s[0:1]
	s_and_b64 s[0:1], s[0:1], s[50:51]
	v_cmp_gt_i32_e64 s[46:47], 40, v169
	v_cndmask_b32_e64 v72, v72, v175, s[0:1]
	s_and_b64 s[0:1], s[0:1], s[48:49]
	v_cmp_gt_i32_e64 s[44:45], 35, v169
	v_cndmask_b32_e64 v71, v71, v175, s[0:1]
	s_and_b64 s[0:1], s[0:1], s[46:47]
	v_cmp_gt_i32_e64 s[42:43], 34, v169
	v_cndmask_b32_e64 v70, v70, v175, s[0:1]
	s_and_b64 s[0:1], s[0:1], s[44:45]
	v_cmp_gt_i32_e64 s[40:41], 33, v169
	v_cndmask_b32_e64 v69, v69, v175, s[0:1]
	s_and_b64 s[0:1], s[0:1], s[42:43]
	v_cmp_gt_i32_e32 vcc, 32, v169
	v_cndmask_b32_e64 v68, v68, v175, s[0:1]
	s_and_b64 s[0:1], s[0:1], s[40:41]
	s_and_b64 vcc, s[0:1], vcc
	v_cndmask_b32_e64 v97, v97, v175, s[94:95]
	v_cndmask_b32_e64 v96, v96, v175, s[92:93]
	v_cndmask_b32_e64 v95, v95, v175, s[90:91]
	v_cndmask_b32_e64 v94, v94, v175, s[88:89]
	v_cndmask_b32_e64 v93, v93, v175, s[86:87]
	v_cndmask_b32_e64 v92, v92, v175, s[84:85]
	v_cndmask_b32_e64 v91, v91, v175, s[82:83]
	v_cndmask_b32_e64 v90, v90, v175, s[80:81]
	v_cndmask_b32_e64 v89, v89, v175, s[78:79]
	v_cndmask_b32_e64 v88, v88, v175, s[76:77]
	v_cndmask_b32_e64 v87, v87, v175, s[74:75]
	v_cndmask_b32_e64 v86, v86, v175, s[72:73]
	v_cndmask_b32_e64 v85, v85, v175, s[70:71]
	v_cndmask_b32_e64 v84, v84, v175, s[68:69]
	v_cndmask_b32_e64 v83, v83, v175, s[2:3]
	v_cndmask_b32_e64 v67, v67, v175, s[0:1]
	v_cndmask_b32_e32 v66, v66, v175, vcc

.LBB0_1414:
	s_ashr_i32 s4, s34, 5
	v_readlane_b32 s0, v243, 52
	s_add_i32 s0, s4, s0
	s_ashr_i32 s1, s0, 31
	s_and_b32 s2, s29, 0xe0000
	s_lshl_b64 s[0:1], s[0:1], 20
	s_or_b32 s0, s0, s2
	s_lshl_b64 s[0:1], s[0:1], 1
	v_readlane_b32 s2, v245, 20
	s_add_u32 s2, s2, s0
	v_readlane_b32 s3, v245, 23
	s_addc_u32 s5, s3, s1
	s_and_b32 s3, s28, 0x180
	s_waitcnt vmcnt(0)
	v_mov_b32_e32 v155, v0
	s_lshl_b32 s3, s3, 1
	s_add_u32 s18, s2, s3
	v_ashrrev_i32_e32 v146, 4, v155
	v_lshlrev_b32_e32 v2, 3, v155
	v_and_b32_e32 v4, 0xfffff0, v146
	v_lshlrev_b32_e32 v5, 1, v146
	s_addc_u32 s19, s5, 0
	s_ashr_i32 s5, s4, 31
	v_and_b32_e32 v3, 0x78, v2
	v_and_or_b32 v4, v5, 8, v4
	v_lshrrev_b32_e32 v5, 1, v146
	v_and_b32_e32 v6, 3, v146
	v_add_u32_e32 v8, 32, v146
	s_lshl_b64 s[4:5], s[4:5], 19
	v_and_or_b32 v5, v5, 4, v6
	s_waitcnt vmcnt(0) lgkmcnt(0)
	v_lshlrev_b32_e32 v50, 1, v3
	v_and_b32_e32 v3, 0xfffff0, v8
	v_lshlrev_b32_e32 v6, 1, v8
	s_add_u32 s2, s22, s4
	v_and_or_b32 v3, v6, 8, v3
	s_addc_u32 s5, s23, s5
	v_lshrrev_b32_e32 v4, 1, v4
	v_bfe_u32 v2, v2, 5, 2
	v_lshrrev_b32_e32 v3, 1, v3
	s_add_u32 s4, s2, s3
	v_readfirstlane_b32 s2, v155
	v_or_b32_e32 v4, v4, v2
	v_or_b32_e32 v2, v3, v2
	s_addc_u32 s5, s5, 0
	s_ashr_i32 s35, s2, 6
	v_and_b32_e32 v1, 63, v155
	s_and_b32 s2, s2, 0x3fffffc0
	v_lshlrev_b32_e32 v6, 9, v2
	v_lshlrev_b32_e32 v2, 8, v146
	v_and_b32_e32 v3, 0x70, v155
	v_lshlrev_b32_e32 v154, 4, v155
	s_lshl_b32 s2, s2, 2
	v_bitop3_b32 v20, v50, v2, v3 bitop3:0xde
	v_lshlrev_b32_e32 v2, 3, v1
	v_and_b32_e32 v3, 0xc0, v154
	v_lshlrev_b32_e32 v7, 1, v155
	v_and_b32_e32 v156, 31, v155
	s_add_i32 s42, s2, 0
	v_and_or_b32 v3, v2, 24, v3
	v_and_b32_e32 v7, 32, v7
	v_and_b32_e32 v2, 0x100, v2
	s_lshl_b32 s2, s35, 5
	v_or3_b32 v7, v3, v7, v2
	v_or_b32_e32 v2, s2, v156
	v_ashrrev_i32_e32 v3, 31, v2
	v_bfe_u32 v157, v155, 5, 1
	v_lshlrev_b64 v[2:3], 10, v[2:3]
	v_lshl_add_u64 v[2:3], s[18:19], 0, v[2:3]
	v_lshlrev_b32_e32 v162, 4, v157
	v_lshl_add_u64 v[2:3], v[2:3], 0, v[162:163]
	v_ashrrev_i32_e32 v147, 31, v146
	v_ashrrev_i32_e32 v9, 31, v8
	v_lshlrev_b32_e32 v4, 9, v4
	v_lshlrev_b32_e32 v5, 6, v5
	global_load_dwordx4 v[126:129], v[2:3], off
	global_load_dwordx4 v[122:125], v[2:3], off offset:32
	global_load_dwordx4 v[118:121], v[2:3], off offset:64
	global_load_dwordx4 v[114:117], v[2:3], off offset:96
	global_load_dwordx4 v[110:113], v[2:3], off offset:128
	global_load_dwordx4 v[106:109], v[2:3], off offset:160
	global_load_dwordx4 v[102:105], v[2:3], off offset:192
	global_load_dwordx4 v[98:101], v[2:3], off offset:224
	v_and_b32_e32 v2, 48, v50
	v_lshlrev_b64 v[52:53], 11, v[146:147]
	v_lshlrev_b64 v[8:9], 11, v[8:9]
	v_or3_b32 v21, v4, v5, v2
	v_or3_b32 v22, v6, v5, v2
	v_mov_b32_e32 v51, v163
	v_lshl_add_u64 v[2:3], s[4:5], 0, v[52:53]
	v_lshl_add_u64 v[8:9], s[4:5], 0, v[8:9]
	v_lshl_add_u64 v[2:3], v[2:3], 0, v[50:51]
	v_lshl_add_u64 v[16:17], v[8:9], 0, v[50:51]
	v_add_u32_e32 v158, 0, v7
	global_load_dwordx4 v[4:7], v[2:3], off offset:1024
	global_load_dwordx4 v[8:11], v[16:17], off offset:1024
	global_load_dwordx4 v[12:15], v[2:3], off
	s_nop 0
	global_load_dwordx4 v[16:19], v[16:17], off
	v_add_u32_e32 v165, 0, v20
	v_add_u32_e32 v166, 0, v21
	s_mov_b64 s[8:9], 0x20000
	v_add_u32_e32 v167, 0, v22
	s_add_i32 s42, s42, 0x10000
	s_waitcnt vmcnt(1)
	ds_write_b128 v165, v[12:15] offset:32768
	s_waitcnt vmcnt(0)
	ds_write_b128 v165, v[16:19] offset:40960
	ds_write_b128 v166, v[4:7]
	v_lshl_add_u64 v[4:5], v[2:3], 0, s[8:9]
	s_mov_b64 s[8:9], 0x30000
	ds_write_b128 v167, v[8:11]
	s_waitcnt lgkmcnt(0)
	s_barrier
	global_load_dwordx4 v[34:37], v[4:5], off offset:1024
	v_lshl_add_u64 v[4:5], v[2:3], 0, s[8:9]
	s_mov_b32 s8, 0x20000
	global_load_dwordx4 v[38:41], v[4:5], off offset:1024
	v_add_co_u32_e32 v4, vcc, s8, v2
	s_mov_b32 s8, 0x30000
	s_nop 0
	v_addc_co_u32_e32 v5, vcc, 0, v3, vcc
	v_add_co_u32_e32 v2, vcc, s8, v2
	global_load_dwordx4 v[42:45], v[4:5], off
	s_nop 0
	v_addc_co_u32_e32 v3, vcc, 0, v3, vcc
	global_load_dwordx4 v[46:49], v[2:3], off
	s_movk_i32 s8, 0x70
	v_and_b32_e32 v2, 0x70, v154
	v_lshl_add_u32 v3, v156, 8, 0
	v_bitop3_b32 v4, v162, v154, s8 bitop3:0x78
	v_add_u32_e32 v168, v3, v4
	v_bitop3_b32 v4, v162, v2, 32 bitop3:0x36
	s_movk_i32 s8, 0x60
	v_add_u32_e32 v164, v3, v4
	v_bitop3_b32 v4, v162, v2, 64 bitop3:0x36
	v_bitop3_b32 v2, v162, v2, s8 bitop3:0x36
	v_add_u32_e32 v161, v3, v4
	v_add_u32_e32 v160, v3, v2
	ds_read_b128 v[2:5], v168 offset:32768
	ds_read_b128 v[18:21], v168 offset:40960
	s_waitcnt lgkmcnt(1)
	v_mfma_f32_32x32x16_bf16 v[2:17], v[2:5], v[126:129], 0
	ds_read_b128 v[54:57], v164 offset:32768
	ds_read_b128 v[58:61], v164 offset:40960
	v_lshl_add_u64 v[148:149], s[4:5], 0, v[50:51]
	s_mov_b64 s[4:5], 0x40000
	v_cmp_gt_u32_e64 s[38:39], 32, v1
	v_lshl_add_u32 v159, v156, 2, s42
	s_waitcnt lgkmcnt(2)
	v_mfma_f32_32x32x16_bf16 v[18:33], v[18:21], v[126:129], 0
	s_waitcnt lgkmcnt(1)
	v_mfma_f32_32x32x16_bf16 v[2:17], v[54:57], v[122:125], v[2:17]
	s_waitcnt lgkmcnt(0)
	v_mfma_f32_32x32x16_bf16 v[18:33], v[58:61], v[122:125], v[18:33]
	ds_read_b128 v[54:57], v161 offset:32768
	ds_read_b128 v[58:61], v161 offset:40960
	s_waitcnt lgkmcnt(1)
	v_mfma_f32_32x32x16_bf16 v[2:17], v[54:57], v[118:121], v[2:17]
	s_waitcnt lgkmcnt(0)
	v_mfma_f32_32x32x16_bf16 v[18:33], v[58:61], v[118:121], v[18:33]
	ds_read_b128 v[54:57], v160 offset:32768
	ds_read_b128 v[58:61], v160 offset:40960
	s_waitcnt lgkmcnt(1)
	v_mfma_f32_32x32x16_bf16 v[2:17], v[54:57], v[114:117], v[2:17]
	s_waitcnt lgkmcnt(0)
	v_mfma_f32_32x32x16_bf16 v[18:33], v[58:61], v[114:117], v[18:33]
	ds_read_b128 v[54:57], v168 offset:32896
	ds_read_b128 v[58:61], v168 offset:41088
	s_waitcnt lgkmcnt(1)
	v_mfma_f32_32x32x16_bf16 v[2:17], v[54:57], v[110:113], v[2:17]
	s_waitcnt lgkmcnt(0)
	v_mfma_f32_32x32x16_bf16 v[18:33], v[58:61], v[110:113], v[18:33]
	ds_read_b128 v[54:57], v164 offset:32896
	ds_read_b128 v[58:61], v164 offset:41088
	s_waitcnt lgkmcnt(1)
	v_mfma_f32_32x32x16_bf16 v[2:17], v[54:57], v[106:109], v[2:17]
	s_waitcnt lgkmcnt(0)
	v_mfma_f32_32x32x16_bf16 v[18:33], v[58:61], v[106:109], v[18:33]
	ds_read_b128 v[54:57], v161 offset:32896
	ds_read_b128 v[58:61], v161 offset:41088
	s_waitcnt lgkmcnt(1)
	v_mfma_f32_32x32x16_bf16 v[2:17], v[54:57], v[102:105], v[2:17]
	s_waitcnt lgkmcnt(0)
	v_mfma_f32_32x32x16_bf16 v[18:33], v[58:61], v[102:105], v[18:33]
	ds_read_b128 v[54:57], v160 offset:32896
	ds_read_b128 v[58:61], v160 offset:41088
	s_waitcnt vmcnt(1)
	ds_write_b128 v165, v[42:45] offset:49152
	s_waitcnt vmcnt(0)
	ds_write_b128 v165, v[46:49] offset:57344
	ds_write_b128 v166, v[34:37] offset:16384
	ds_write_b128 v167, v[38:41] offset:16384
	v_lshl_add_u64 v[34:35], v[148:149], 0, v[52:53]
	v_lshl_add_u64 v[36:37], v[34:35], 0, s[4:5]
	s_mov_b64 s[4:5], 0x50000
	s_waitcnt lgkmcnt(0)
	s_barrier
	v_mfma_f32_32x32x16_bf16 v[2:17], v[54:57], v[98:101], v[2:17]
	global_load_dwordx4 v[130:133], v[36:37], off offset:1024
	v_lshl_add_u64 v[36:37], v[34:35], 0, s[4:5]
	s_mov_b32 s4, 0x40000
	global_load_dwordx4 v[134:137], v[36:37], off offset:1024
	s_nop 7
	v_max_f32_e32 v54, v3, v3
	v_max_f32_e32 v55, v2, v2
	v_mfma_f32_32x32x16_bf16 v[18:33], v[58:61], v[98:101], v[18:33]
	v_max_f32_e32 v54, v55, v54
	v_max3_f32 v54, v54, v4, v5
	v_max3_f32 v54, v54, v6, v7
	v_max3_f32 v54, v54, v8, v9
	v_max3_f32 v54, v54, v10, v11
	v_max3_f32 v54, v54, v12, v13
	v_max3_f32 v54, v54, v14, v15
	v_max3_f32 v54, v54, v16, v17
	s_nop 3
	v_max3_f32 v54, v54, v18, v19
	v_max3_f32 v54, v54, v20, v21
	v_max3_f32 v54, v54, v22, v23
	v_max3_f32 v54, v54, v24, v25
	v_max3_f32 v54, v54, v26, v27
	v_max3_f32 v54, v54, v28, v29
	v_max3_f32 v54, v54, v30, v31
	v_max3_f32 v54, v54, v32, v33
	v_mov_b32_e32 v55, v54
	s_nop 1
	v_permlane32_swap_b32_e32 v54, v55
	v_max_f32_e32 v55, v55, v55
	v_max_f32_e32 v54, v54, v54
	v_max_f32_e32 v54, v54, v55
	v_add_f32_e32 v55, 0x7149f2ca, v54
	v_mul_f32_e32 v55, 0x3e0293ee, v55
	v_cmp_ge_f32_e32 vcc, s24, v55
	s_cmp_eq_u64 vcc, exec
	v_add_co_u32_e32 v36, vcc, s4, v34
	s_mov_b32 s4, 0x50000
	s_nop 0
	v_addc_co_u32_e32 v37, vcc, 0, v35, vcc
	v_add_co_u32_e32 v34, vcc, s4, v34
	global_load_dwordx4 v[138:141], v[36:37], off
	s_nop 0
	v_addc_co_u32_e32 v35, vcc, 0, v35, vcc
	global_load_dwordx4 v[142:145], v[34:35], off
	s_cselect_b64 s[36:37], -1, 0
	v_max_f32_e32 v151, 0xf149f2ca, v54
	v_cndmask_b32_e64 v150, v151, v177, s[36:37]
	v_mul_f32_e32 v54, 0xbe0293ee, v150
	v_fmamk_f32 v2, v2, 0x3e0293ee, v54
	v_fmamk_f32 v3, v3, 0x3e0293ee, v54
	v_fmamk_f32 v4, v4, 0x3e0293ee, v54
	v_fmamk_f32 v5, v5, 0x3e0293ee, v54
	v_fmamk_f32 v6, v6, 0x3e0293ee, v54
	v_fmamk_f32 v7, v7, 0x3e0293ee, v54
	v_fmamk_f32 v8, v8, 0x3e0293ee, v54
	v_fmamk_f32 v9, v9, 0x3e0293ee, v54
	v_fmamk_f32 v55, v10, 0x3e0293ee, v54
	v_fmamk_f32 v56, v11, 0x3e0293ee, v54
	v_fmamk_f32 v57, v12, 0x3e0293ee, v54
	v_fmamk_f32 v58, v13, 0x3e0293ee, v54
	v_fmamk_f32 v59, v14, 0x3e0293ee, v54
	v_fmamk_f32 v60, v15, 0x3e0293ee, v54
	v_fmamk_f32 v61, v16, 0x3e0293ee, v54
	v_fmamk_f32 v62, v17, 0x3e0293ee, v54
	v_exp_f32_e32 v10, v2
	v_exp_f32_e32 v11, v3
	v_exp_f32_e32 v12, v4
	v_exp_f32_e32 v13, v5
	v_exp_f32_e32 v14, v6
	v_exp_f32_e32 v15, v7
	v_exp_f32_e32 v16, v8
	v_exp_f32_e32 v17, v9
	v_exp_f32_e32 v2, v55
	v_exp_f32_e32 v3, v56
	v_exp_f32_e32 v4, v57
	v_exp_f32_e32 v5, v58
	v_exp_f32_e32 v6, v59
	v_exp_f32_e32 v7, v60
	v_exp_f32_e32 v8, v61
	v_exp_f32_e32 v9, v62
	v_fmamk_f32 v18, v18, 0x3e0293ee, v54
	v_fmamk_f32 v19, v19, 0x3e0293ee, v54
	v_fmamk_f32 v20, v20, 0x3e0293ee, v54
	v_fmamk_f32 v21, v21, 0x3e0293ee, v54
	v_fmamk_f32 v22, v22, 0x3e0293ee, v54
	v_fmamk_f32 v23, v23, 0x3e0293ee, v54
	v_fmamk_f32 v24, v24, 0x3e0293ee, v54
	v_fmamk_f32 v25, v25, 0x3e0293ee, v54
	v_fmamk_f32 v26, v26, 0x3e0293ee, v54
	v_fmamk_f32 v27, v27, 0x3e0293ee, v54
	v_fmamk_f32 v28, v28, 0x3e0293ee, v54
	v_fmamk_f32 v29, v29, 0x3e0293ee, v54
	v_fmamk_f32 v30, v30, 0x3e0293ee, v54
	v_fmamk_f32 v31, v31, 0x3e0293ee, v54
	v_fmamk_f32 v32, v32, 0x3e0293ee, v54
	v_fmac_f32_e32 v54, 0x3e0293ee, v33
	ds_read_b128 v[228:231], v168 offset:49152
	ds_read_b128 v[232:235], v168 offset:57344
	ds_read_b128 v[236:239], v164 offset:49152
	ds_read_b128 v[248:251], v164 offset:57344
	ds_read_b128 v[252:255], v161 offset:49152
	s_waitcnt lgkmcnt(4)
	v_mfma_f32_32x32x16_bf16 v[82:97], v[228:231], v[126:129], 0
	ds_read_b128 v[228:231], v161 offset:57344
	v_add_f32_e32 v34, 0, v10
	v_add_f32_e32 v34, v11, v34
	v_add_f32_e32 v34, v12, v34
	v_add_f32_e32 v34, v13, v34
	v_add_f32_e32 v34, v14, v34
	s_waitcnt lgkmcnt(4)
	v_mfma_f32_32x32x16_bf16 v[66:81], v[232:235], v[126:129], 0
	ds_read_b128 v[232:235], v160 offset:49152
	v_add_f32_e32 v34, v15, v34
	v_add_f32_e32 v34, v16, v34
	v_add_f32_e32 v34, v17, v34
	v_add_f32_e32 v34, v2, v34
	v_add_f32_e32 v34, v3, v34
	s_waitcnt lgkmcnt(4)
	v_mfma_f32_32x32x16_bf16 v[82:97], v[236:239], v[122:125], v[82:97]
	ds_read_b128 v[236:239], v160 offset:57344
	v_add_f32_e32 v34, v4, v34
	v_add_f32_e32 v34, v5, v34
	v_exp_f32_e32 v18, v18
	v_add_f32_e32 v34, v6, v34
	v_exp_f32_e32 v19, v19
	s_waitcnt lgkmcnt(4)
	v_mfma_f32_32x32x16_bf16 v[66:81], v[248:251], v[122:125], v[66:81]
	ds_read_b128 v[248:251], v168 offset:49280
	v_add_f32_e32 v34, v7, v34
	v_exp_f32_e32 v20, v20
	v_add_f32_e32 v34, v8, v34
	v_exp_f32_e32 v21, v21
	v_add_f32_e32 v34, v9, v34
	s_waitcnt lgkmcnt(4)
	v_mfma_f32_32x32x16_bf16 v[82:97], v[252:255], v[118:121], v[82:97]
	ds_read_b128 v[252:255], v168 offset:57472
	v_exp_f32_e32 v22, v22
	v_add_f32_e32 v34, v18, v34
	v_exp_f32_e32 v23, v23
	v_add_f32_e32 v34, v19, v34
	v_exp_f32_e32 v24, v24
	s_waitcnt lgkmcnt(4)
	v_mfma_f32_32x32x16_bf16 v[66:81], v[228:231], v[118:121], v[66:81]
	ds_read_b128 v[228:231], v164 offset:49280
	v_add_f32_e32 v34, v20, v34
	v_exp_f32_e32 v25, v25
	v_add_f32_e32 v34, v21, v34
	v_exp_f32_e32 v26, v26
	v_add_f32_e32 v34, v22, v34
	s_waitcnt lgkmcnt(4)
	v_mfma_f32_32x32x16_bf16 v[82:97], v[232:235], v[114:117], v[82:97]
	ds_read_b128 v[232:235], v164 offset:57472
	v_exp_f32_e32 v27, v27
	v_add_f32_e32 v34, v23, v34
	v_exp_f32_e32 v28, v28
	v_add_f32_e32 v34, v24, v34
	v_exp_f32_e32 v29, v29
	s_waitcnt lgkmcnt(4)
	v_mfma_f32_32x32x16_bf16 v[66:81], v[236:239], v[114:117], v[66:81]
	ds_read_b128 v[236:239], v161 offset:49280
	v_add_f32_e32 v34, v25, v34
	v_exp_f32_e32 v30, v30
	v_add_f32_e32 v34, v26, v34
	v_exp_f32_e32 v31, v31
	v_add_f32_e32 v34, v27, v34
	s_waitcnt lgkmcnt(4)
	v_mfma_f32_32x32x16_bf16 v[82:97], v[248:251], v[110:113], v[82:97]
	ds_read_b128 v[248:251], v161 offset:57472
	v_exp_f32_e32 v32, v32
	v_add_f32_e32 v34, v28, v34
	v_exp_f32_e32 v33, v54
	v_add_f32_e32 v34, v29, v34
	v_add_f32_e32 v34, v30, v34
	s_waitcnt lgkmcnt(4)
	v_mfma_f32_32x32x16_bf16 v[66:81], v[252:255], v[110:113], v[66:81]
	ds_read_b128 v[252:255], v160 offset:49280
	v_add_f32_e32 v34, v31, v34
	v_add_f32_e32 v34, v32, v34
	v_add_f32_e32 v169, v33, v34
	v_mov_b32_e32 v179, v169
	v_cvt_pk_bf16_f32 v50, v10, v11
	s_waitcnt lgkmcnt(4)
	v_mfma_f32_32x32x16_bf16 v[82:97], v[228:231], v[106:109], v[82:97]
	ds_read_b128 v[228:231], v160 offset:57472
	v_cvt_pk_bf16_f32 v51, v12, v13
	v_cvt_pk_bf16_f32 v52, v14, v15
	v_cvt_pk_bf16_f32 v53, v16, v17
	v_cvt_pk_bf16_f32 v180, v2, v3
	v_cvt_pk_bf16_f32 v181, v4, v5
	s_waitcnt lgkmcnt(4)
	v_mfma_f32_32x32x16_bf16 v[66:81], v[232:235], v[106:109], v[66:81]
	v_cvt_pk_bf16_f32 v182, v6, v7
	s_nop 1
	v_permlane32_swap_b32_e32 v169, v179
	v_permlane32_swap_b32_e32 v50, v52
	v_permlane32_swap_b32_e32 v51, v53
	s_waitcnt lgkmcnt(3)
	v_mfma_f32_32x32x16_bf16 v[82:97], v[236:239], v[102:105], v[82:97]
	v_cvt_pk_bf16_f32 v183, v8, v9
	v_permlane32_swap_b32_e32 v180, v182
	v_cvt_pk_bf16_f32 v184, v18, v19
	v_cvt_pk_bf16_f32 v185, v20, v21
	v_cvt_pk_bf16_f32 v186, v22, v23
	s_waitcnt lgkmcnt(2)
	v_mfma_f32_32x32x16_bf16 v[66:81], v[248:251], v[102:105], v[66:81]
	v_cvt_pk_bf16_f32 v187, v24, v25
	v_cvt_pk_bf16_f32 v188, v26, v27
	v_cvt_pk_bf16_f32 v189, v28, v29
	v_cvt_pk_bf16_f32 v190, v30, v31
	v_cvt_pk_bf16_f32 v191, v32, v33
	s_waitcnt lgkmcnt(1)
	v_mfma_f32_32x32x16_bf16 v[82:97], v[252:255], v[98:101], v[82:97]
	v_permlane32_swap_b32_e32 v181, v183
	v_permlane32_swap_b32_e32 v184, v186
	v_permlane32_swap_b32_e32 v185, v187
	v_permlane32_swap_b32_e32 v188, v190
	v_permlane32_swap_b32_e32 v189, v191
	s_waitcnt lgkmcnt(0)
	v_mfma_f32_32x32x16_bf16 v[66:81], v[228:231], v[98:101], v[66:81]
	ds_read_b64_tr_b16 v[2:3], v158 offset:0
	ds_read_b64_tr_b16 v[4:5], v158 offset:0x800
	ds_read_b64_tr_b16 v[18:19], v158 offset:0x1000
	ds_read_b64_tr_b16 v[20:21], v158 offset:0x1800
	ds_read_b64_tr_b16 v[22:23], v158 offset:0x2000
	ds_read_b64_tr_b16 v[24:25], v158 offset:0x2800
	ds_read_b64_tr_b16 v[26:27], v158 offset:0x3000
	ds_read_b64_tr_b16 v[28:29], v158 offset:0x3800
	s_nop 0
	s_waitcnt lgkmcnt(6)
	v_mfma_f32_32x32x16_bf16 v[2:17], v[50:53], v[2:5], 0
	s_waitcnt lgkmcnt(4)
	v_mfma_f32_32x32x16_bf16 v[2:17], v[180:183], v[18:21], v[2:17]
	ds_read_b64_tr_b16 v[18:19], v158 offset:0x200
	ds_read_b64_tr_b16 v[20:21], v158 offset:0xa00
	ds_read_b64_tr_b16 v[34:35], v158 offset:0x1200
	ds_read_b64_tr_b16 v[36:37], v158 offset:0x1a00
	ds_read_b64_tr_b16 v[38:39], v158 offset:0x2200
	ds_read_b64_tr_b16 v[40:41], v158 offset:0x2a00
	ds_read_b64_tr_b16 v[42:43], v158 offset:0x3200
	s_waitcnt lgkmcnt(9)
	v_mfma_f32_32x32x16_bf16 v[2:17], v[184:187], v[22:25], v[2:17]
	ds_read_b64_tr_b16 v[44:45], v158 offset:0x3a00
	s_waitcnt lgkmcnt(8)
	v_mfma_f32_32x32x16_bf16 v[2:17], v[188:191], v[26:29], v[2:17]
	s_waitcnt lgkmcnt(6)
	v_mfma_f32_32x32x16_bf16 v[18:33], v[50:53], v[18:21], 0
	s_waitcnt lgkmcnt(4)
	v_mfma_f32_32x32x16_bf16 v[18:33], v[180:183], v[34:37], v[18:33]
	ds_read_b64_tr_b16 v[34:35], v158 offset:0x400
	ds_read_b64_tr_b16 v[36:37], v158 offset:0xc00
	ds_read_b64_tr_b16 v[54:55], v158 offset:0x1400
	ds_read_b64_tr_b16 v[56:57], v158 offset:0x1c00
	ds_read_b64_tr_b16 v[58:59], v158 offset:0x2400
	ds_read_b64_tr_b16 v[60:61], v158 offset:0x2c00
	ds_read_b64_tr_b16 v[62:63], v158 offset:0x3400
	s_waitcnt lgkmcnt(9)
	v_mfma_f32_32x32x16_bf16 v[18:33], v[184:187], v[38:41], v[18:33]
	ds_read_b64_tr_b16 v[64:65], v158 offset:0x3c00
	s_waitcnt lgkmcnt(8)
	v_mfma_f32_32x32x16_bf16 v[18:33], v[188:191], v[42:45], v[18:33]
	s_waitcnt lgkmcnt(6)
	v_mfma_f32_32x32x16_bf16 v[34:49], v[50:53], v[34:37], 0
	s_waitcnt lgkmcnt(4)
	v_mfma_f32_32x32x16_bf16 v[34:49], v[180:183], v[54:57], v[34:49]
	ds_read_b64_tr_b16 v[54:55], v158 offset:0x600
	ds_read_b64_tr_b16 v[56:57], v158 offset:0xe00
	ds_read_b64_tr_b16 v[192:193], v158 offset:0x1600
	ds_read_b64_tr_b16 v[194:195], v158 offset:0x1e00
	ds_read_b64_tr_b16 v[196:197], v158 offset:0x2600
	ds_read_b64_tr_b16 v[198:199], v158 offset:0x2e00
	ds_read_b64_tr_b16 v[200:201], v158 offset:0x3600
	s_waitcnt lgkmcnt(9)
	v_mfma_f32_32x32x16_bf16 v[34:49], v[184:187], v[58:61], v[34:49]
	ds_read_b64_tr_b16 v[202:203], v158 offset:0x3e00
	s_waitcnt lgkmcnt(8)
	v_mfma_f32_32x32x16_bf16 v[34:49], v[188:191], v[62:65], v[34:49]
	s_waitcnt lgkmcnt(6)
	v_mfma_f32_32x32x16_bf16 v[50:65], v[50:53], v[54:57], 0
	s_waitcnt lgkmcnt(4)
	v_mfma_f32_32x32x16_bf16 v[50:65], v[180:183], v[192:195], v[50:65]
	s_waitcnt lgkmcnt(2)
	v_mfma_f32_32x32x16_bf16 v[50:65], v[184:187], v[196:199], v[50:65]
	s_waitcnt lgkmcnt(0)
	v_mfma_f32_32x32x16_bf16 v[50:65], v[188:191], v[200:203], v[50:65]
	v_max_f32_e32 v152, v83, v83
	v_max_f32_e32 v153, v82, v82
	v_max_f32_e32 v152, v153, v152
	v_max3_f32 v152, v152, v84, v85
	v_max3_f32 v152, v152, v86, v87
	v_max3_f32 v152, v152, v88, v89
	v_max3_f32 v152, v152, v90, v91
	v_max3_f32 v152, v152, v92, v93
	v_max3_f32 v152, v152, v94, v95
	v_max3_f32 v152, v152, v96, v97
	v_max3_f32 v152, v152, v66, v67
	v_max3_f32 v152, v152, v68, v69
	v_max3_f32 v152, v152, v70, v71
	v_max3_f32 v152, v152, v72, v73
	v_max3_f32 v152, v152, v74, v75
	v_max3_f32 v152, v152, v76, v77
	v_max3_f32 v152, v152, v78, v79
	v_max3_f32 v152, v152, v80, v81
	v_mov_b32_e32 v153, v152
	s_nop 1
	v_permlane32_swap_b32_e32 v152, v153
	v_max_f32_e32 v153, v153, v153
	v_max_f32_e32 v152, v152, v152
	v_max_f32_e32 v152, v152, v153
	v_sub_f32_e32 v153, v152, v150
	v_mul_f32_e32 v153, 0x3e0293ee, v153
	v_max_f32_e32 v152, v150, v152
	v_cmp_ge_f32_e32 vcc, s24, v153
	v_sub_f32_e32 v153, v150, v152
	v_mul_f32_e32 v153, 0x3e0293ee, v153
	v_exp_f32_e32 v153, v153
	s_cmp_eq_u64 vcc, exec
	s_cselect_b64 s[40:41], -1, 0
	v_cndmask_b32_e64 v180, v153, 1.0, s[40:41]
	v_cmp_gt_f32_e32 vcc, 1.0, v180
	s_barrier
	s_waitcnt vmcnt(1)
	ds_write_b128 v165, v[138:141] offset:32768
	s_waitcnt vmcnt(0)
	ds_write_b128 v165, v[142:145] offset:40960
	ds_write_b128 v166, v[130:133]
	ds_write_b128 v167, v[134:137]
	s_cbranch_vccz .LBB0_1418
	s_and_saveexec_b64 s[4:5], s[38:39]
	ds_write_b32 v159, v180 offset:128
	s_or_b64 exec, exec, s[4:5]
	s_waitcnt lgkmcnt(0)
	v_add_u32_e32 v142, s42, v162
	ds_read_b128 v[130:133], v142 offset:224
	ds_read_b128 v[134:137], v142 offset:192
	ds_read_b128 v[138:141], v142 offset:160
	ds_read_b128 v[142:145], v142 offset:128
	s_waitcnt lgkmcnt(3)
	v_pk_mul_f32 v[14:15], v[14:15], v[130:131]
	s_waitcnt lgkmcnt(2)
	v_pk_mul_f32 v[10:11], v[10:11], v[134:135]
	s_waitcnt lgkmcnt(1)
	v_pk_mul_f32 v[6:7], v[6:7], v[138:139]
	v_pk_mul_f32 v[16:17], v[16:17], v[132:133]
	v_pk_mul_f32 v[12:13], v[12:13], v[136:137]
	v_pk_mul_f32 v[8:9], v[8:9], v[140:141]
	s_waitcnt lgkmcnt(0)
	v_pk_mul_f32 v[4:5], v[4:5], v[144:145]
	v_pk_mul_f32 v[2:3], v[2:3], v[142:143]
	v_pk_mul_f32 v[30:31], v[30:31], v[130:131]
	v_pk_mul_f32 v[26:27], v[26:27], v[134:135]
	v_pk_mul_f32 v[22:23], v[22:23], v[138:139]
	v_pk_mul_f32 v[32:33], v[32:33], v[132:133]
	v_pk_mul_f32 v[28:29], v[28:29], v[136:137]
	v_pk_mul_f32 v[24:25], v[24:25], v[140:141]
	v_pk_mul_f32 v[20:21], v[20:21], v[144:145]
	v_pk_mul_f32 v[18:19], v[18:19], v[142:143]
	v_pk_mul_f32 v[46:47], v[46:47], v[130:131]
	v_pk_mul_f32 v[42:43], v[42:43], v[134:135]
	v_pk_mul_f32 v[38:39], v[38:39], v[138:139]
	v_pk_mul_f32 v[48:49], v[48:49], v[132:133]
	v_pk_mul_f32 v[44:45], v[44:45], v[136:137]
	v_pk_mul_f32 v[40:41], v[40:41], v[140:141]
	v_pk_mul_f32 v[36:37], v[36:37], v[144:145]
	v_pk_mul_f32 v[34:35], v[34:35], v[142:143]
	v_pk_mul_f32 v[62:63], v[62:63], v[130:131]
	v_pk_mul_f32 v[58:59], v[58:59], v[134:135]
	v_pk_mul_f32 v[54:55], v[54:55], v[138:139]
	v_pk_mul_f32 v[64:65], v[64:65], v[132:133]
	v_pk_mul_f32 v[60:61], v[60:61], v[136:137]
	v_pk_mul_f32 v[56:57], v[56:57], v[140:141]
	v_pk_mul_f32 v[52:53], v[52:53], v[144:145]
	v_pk_mul_f32 v[50:51], v[50:51], v[142:143]
.LBB0_1418:
	v_cndmask_b32_e64 v184, v152, v150, s[40:41]
	v_mul_f32_e32 v182, 0xbe0293ee, v184
	v_fmamk_f32 v183, v66, 0x3e0293ee, v182
	v_fmamk_f32 v66, v83, 0x3e0293ee, v182
	v_fmamk_f32 v197, v67, 0x3e0293ee, v182
	v_fmamk_f32 v67, v84, 0x3e0293ee, v182
	v_exp_f32_e32 v196, v66
	v_exp_f32_e32 v192, v67
	v_lshlrev_b64 v[66:67], 11, v[146:147]
	v_sub_f32_e32 v130, 0xf149f2ca, v151
	v_fmamk_f32 v198, v68, 0x3e0293ee, v182
	v_fmamk_f32 v68, v85, 0x3e0293ee, v182
	v_fmamk_f32 v199, v69, 0x3e0293ee, v182
	v_fmamk_f32 v69, v86, 0x3e0293ee, v182
	v_lshl_add_u64 v[66:67], v[148:149], 0, v[66:67]
	s_mov_b64 s[4:5], 0x60000
	v_mul_f32_e32 v130, 0x3e0293ee, v130
	v_fmamk_f32 v200, v70, 0x3e0293ee, v182
	v_fmamk_f32 v70, v87, 0x3e0293ee, v182
	v_fmamk_f32 v201, v71, 0x3e0293ee, v182
	v_fmamk_f32 v71, v88, 0x3e0293ee, v182
	v_exp_f32_e32 v195, v68
	v_exp_f32_e32 v190, v69
	v_lshl_add_u64 v[68:69], v[66:67], 0, s[4:5]
	s_mov_b64 s[4:5], 0x70000
	v_exp_f32_e32 v181, v130
	v_exp_f32_e32 v193, v70
	v_exp_f32_e32 v189, v71
	s_waitcnt lgkmcnt(0)
	s_barrier
	v_lshl_add_u64 v[70:71], v[66:67], 0, s[4:5]
	global_load_dwordx4 v[130:133], v[68:69], off offset:1024
	global_load_dwordx4 v[134:137], v[70:71], off offset:1024
	v_add_co_u32_e32 v68, vcc, 0x60000, v66
	s_mov_b32 s4, 0x70000
	s_nop 0
	v_addc_co_u32_e32 v69, vcc, 0, v67, vcc
	v_add_co_u32_e32 v66, vcc, s4, v66
	v_fmamk_f32 v82, v82, 0x3e0293ee, v182
	s_nop 0
	v_addc_co_u32_e32 v67, vcc, 0, v67, vcc
	global_load_dwordx4 v[138:141], v[68:69], off
	global_load_dwordx4 v[142:145], v[66:67], off
	v_fmamk_f32 v202, v72, 0x3e0293ee, v182
	v_fmamk_f32 v72, v89, 0x3e0293ee, v182
	v_fmamk_f32 v203, v73, 0x3e0293ee, v182
	v_fmamk_f32 v73, v90, 0x3e0293ee, v182
	v_fmamk_f32 v204, v74, 0x3e0293ee, v182
	v_fmamk_f32 v74, v91, 0x3e0293ee, v182
	v_fmamk_f32 v205, v75, 0x3e0293ee, v182
	v_fmamk_f32 v75, v92, 0x3e0293ee, v182
	v_fmamk_f32 v206, v76, 0x3e0293ee, v182
	v_fmamk_f32 v76, v93, 0x3e0293ee, v182
	v_fmamk_f32 v207, v77, 0x3e0293ee, v182
	v_fmamk_f32 v77, v94, 0x3e0293ee, v182
	v_fmamk_f32 v208, v78, 0x3e0293ee, v182
	v_fmamk_f32 v78, v95, 0x3e0293ee, v182
	v_fmamk_f32 v83, v96, 0x3e0293ee, v182
	v_fmamk_f32 v84, v97, 0x3e0293ee, v182
	v_fmamk_f32 v209, v79, 0x3e0293ee, v182
	v_fmamk_f32 v210, v80, 0x3e0293ee, v182
	v_fmac_f32_e32 v182, 0x3e0293ee, v81
	v_exp_f32_e32 v194, v82
	v_exp_f32_e32 v191, v72
	v_exp_f32_e32 v150, v73
	v_exp_f32_e32 v188, v74
	v_exp_f32_e32 v151, v75
	v_exp_f32_e32 v187, v76
	v_exp_f32_e32 v152, v77
	v_exp_f32_e32 v186, v78
	v_exp_f32_e32 v153, v83
	v_exp_f32_e32 v185, v84
	ds_read_b128 v[228:231], v168 offset:32768
	ds_read_b128 v[232:235], v164 offset:32768
	ds_read_b128 v[236:239], v168 offset:40960
	ds_read_b128 v[248:251], v164 offset:40960
	ds_read_b128 v[252:255], v161 offset:32768
	s_waitcnt lgkmcnt(4)
	v_mfma_f32_32x32x16_bf16 v[82:97], v[228:231], v[126:129], 0
	ds_read_b128 v[228:231], v161 offset:40960
	v_add_f32_e32 v146, 0, v194
	v_add_f32_e32 v146, v196, v146
	v_add_f32_e32 v146, v192, v146
	v_add_f32_e32 v146, v195, v146
	v_add_f32_e32 v146, v190, v146
	s_waitcnt lgkmcnt(4)
	v_mfma_f32_32x32x16_bf16 v[82:97], v[232:235], v[122:125], v[82:97]
	ds_read_b128 v[232:235], v160 offset:32768
	v_add_f32_e32 v146, v193, v146
	v_add_f32_e32 v146, v189, v146
	v_add_f32_e32 v146, v191, v146
	v_add_f32_e32 v146, v150, v146
	v_add_f32_e32 v146, v188, v146
	s_waitcnt lgkmcnt(4)
	v_mfma_f32_32x32x16_bf16 v[66:81], v[236:239], v[126:129], 0
	ds_read_b128 v[236:239], v160 offset:40960
	v_add_f32_e32 v146, v151, v146
	v_add_f32_e32 v146, v187, v146
	v_exp_f32_e32 v211, v183
	v_add_f32_e32 v146, v152, v146
	v_exp_f32_e32 v197, v197
	s_waitcnt lgkmcnt(4)
	v_mfma_f32_32x32x16_bf16 v[66:81], v[248:251], v[122:125], v[66:81]
	ds_read_b128 v[248:251], v168 offset:32896
	v_add_f32_e32 v146, v186, v146
	v_exp_f32_e32 v198, v198
	v_add_f32_e32 v146, v153, v146
	v_exp_f32_e32 v199, v199
	v_add_f32_e32 v146, v185, v146
	s_waitcnt lgkmcnt(4)
	v_mfma_f32_32x32x16_bf16 v[82:97], v[252:255], v[118:121], v[82:97]
	ds_read_b128 v[252:255], v168 offset:41088
	v_exp_f32_e32 v200, v200
	v_add_f32_e32 v146, v211, v146
	v_exp_f32_e32 v201, v201
	v_add_f32_e32 v146, v197, v146
	v_exp_f32_e32 v202, v202
	s_waitcnt lgkmcnt(4)
	v_mfma_f32_32x32x16_bf16 v[66:81], v[228:231], v[118:121], v[66:81]
	ds_read_b128 v[228:231], v164 offset:32896
	v_add_f32_e32 v146, v198, v146
	v_exp_f32_e32 v203, v203
	v_add_f32_e32 v146, v199, v146
	v_exp_f32_e32 v204, v204
	v_add_f32_e32 v146, v200, v146
	s_waitcnt lgkmcnt(4)
	v_mfma_f32_32x32x16_bf16 v[82:97], v[232:235], v[114:117], v[82:97]
	ds_read_b128 v[232:235], v164 offset:41088
	v_exp_f32_e32 v205, v205
	v_add_f32_e32 v146, v201, v146
	v_exp_f32_e32 v206, v206
	v_add_f32_e32 v146, v202, v146
	v_exp_f32_e32 v207, v207
	s_waitcnt lgkmcnt(4)
	v_mfma_f32_32x32x16_bf16 v[66:81], v[236:239], v[114:117], v[66:81]
	ds_read_b128 v[236:239], v161 offset:32896
	v_add_f32_e32 v146, v203, v146
	v_exp_f32_e32 v208, v208
	v_add_f32_e32 v146, v204, v146
	v_exp_f32_e32 v209, v209
	v_add_f32_e32 v146, v205, v146
	s_waitcnt lgkmcnt(4)
	v_mfma_f32_32x32x16_bf16 v[82:97], v[248:251], v[110:113], v[82:97]
	ds_read_b128 v[248:251], v161 offset:41088
	v_exp_f32_e32 v210, v210
	v_add_f32_e32 v146, v206, v146
	v_exp_f32_e32 v212, v182
	v_add_f32_e32 v146, v207, v146
	v_add_f32_e32 v146, v208, v146
	s_waitcnt lgkmcnt(4)
	v_mfma_f32_32x32x16_bf16 v[66:81], v[252:255], v[110:113], v[66:81]
	ds_read_b128 v[252:255], v160 offset:32896
	v_add_f32_e32 v146, v209, v146
	v_add_f32_e32 v146, v210, v146
	v_add_f32_e32 v182, v212, v146
	v_mov_b32_e32 v183, v182
	v_cvt_pk_bf16_f32 v146, v194, v196
	s_waitcnt lgkmcnt(4)
	v_mfma_f32_32x32x16_bf16 v[82:97], v[228:231], v[106:109], v[82:97]
	ds_read_b128 v[228:231], v160 offset:41088
	v_cvt_pk_bf16_f32 v147, v192, v195
	v_cvt_pk_bf16_f32 v148, v190, v193
	v_cvt_pk_bf16_f32 v149, v189, v191
	s_nop 1
	v_permlane32_swap_b32_e32 v182, v183
	s_waitcnt lgkmcnt(4)
	v_mfma_f32_32x32x16_bf16 v[66:81], v[232:235], v[106:109], v[66:81]
	v_permlane32_swap_b32_e32 v146, v148
	v_permlane32_swap_b32_e32 v147, v149
	v_cvt_pk_bf16_f32 v150, v150, v188
	v_cvt_pk_bf16_f32 v151, v151, v187
	v_cvt_pk_bf16_f32 v152, v152, v186
	s_waitcnt lgkmcnt(3)
	v_mfma_f32_32x32x16_bf16 v[82:97], v[236:239], v[102:105], v[82:97]
	v_cvt_pk_bf16_f32 v153, v153, v185
	v_cvt_pk_bf16_f32 v186, v211, v197
	v_cvt_pk_bf16_f32 v187, v198, v199
	v_cvt_pk_bf16_f32 v188, v200, v201
	v_cvt_pk_bf16_f32 v189, v202, v203
	s_waitcnt lgkmcnt(2)
	v_mfma_f32_32x32x16_bf16 v[66:81], v[248:251], v[102:105], v[66:81]
	v_cvt_pk_bf16_f32 v190, v204, v205
	v_cvt_pk_bf16_f32 v191, v206, v207
	v_cvt_pk_bf16_f32 v192, v208, v209
	v_cvt_pk_bf16_f32 v193, v210, v212
	s_nop 0
	s_waitcnt lgkmcnt(1)
	v_mfma_f32_32x32x16_bf16 v[82:97], v[252:255], v[98:101], v[82:97]
	v_permlane32_swap_b32_e32 v150, v152
	v_permlane32_swap_b32_e32 v151, v153
	v_permlane32_swap_b32_e32 v186, v188
	v_permlane32_swap_b32_e32 v187, v189
	v_permlane32_swap_b32_e32 v190, v192
	s_waitcnt lgkmcnt(0)
	v_mfma_f32_32x32x16_bf16 v[66:81], v[228:231], v[98:101], v[66:81]
	v_permlane32_swap_b32_e32 v191, v193
	ds_read_b64_tr_b16 v[194:195], v158 offset:0x4000
	ds_read_b64_tr_b16 v[196:197], v158 offset:0x4800
	ds_read_b64_tr_b16 v[198:199], v158 offset:0x5000
	ds_read_b64_tr_b16 v[200:201], v158 offset:0x5800
	ds_read_b64_tr_b16 v[202:203], v158 offset:0x6000
	ds_read_b64_tr_b16 v[204:205], v158 offset:0x6800
	ds_read_b64_tr_b16 v[206:207], v158 offset:0x7000
	ds_read_b64_tr_b16 v[208:209], v158 offset:0x7800
	s_nop 0
	s_waitcnt lgkmcnt(6)
	v_mfma_f32_32x32x16_bf16 v[2:17], v[146:149], v[194:197], v[2:17]
	ds_read_b64_tr_b16 v[194:195], v158 offset:0x4200
	ds_read_b64_tr_b16 v[196:197], v158 offset:0x4a00
	s_waitcnt lgkmcnt(6)
	v_mfma_f32_32x32x16_bf16 v[2:17], v[150:153], v[198:201], v[2:17]
	ds_read_b64_tr_b16 v[198:199], v158 offset:0x5200
	ds_read_b64_tr_b16 v[200:201], v158 offset:0x5a00
	s_waitcnt lgkmcnt(6)
	v_mfma_f32_32x32x16_bf16 v[2:17], v[186:189], v[202:205], v[2:17]
	ds_read_b64_tr_b16 v[202:203], v158 offset:0x6200
	ds_read_b64_tr_b16 v[204:205], v158 offset:0x6a00
	s_waitcnt lgkmcnt(6)
	v_mfma_f32_32x32x16_bf16 v[2:17], v[190:193], v[206:209], v[2:17]
	ds_read_b64_tr_b16 v[206:207], v158 offset:0x7200
	ds_read_b64_tr_b16 v[208:209], v158 offset:0x7a00
	s_waitcnt lgkmcnt(6)
	v_mfma_f32_32x32x16_bf16 v[18:33], v[146:149], v[194:197], v[18:33]
	ds_read_b64_tr_b16 v[194:195], v158 offset:0x4400
	ds_read_b64_tr_b16 v[196:197], v158 offset:0x4c00
	s_waitcnt lgkmcnt(6)
	v_mfma_f32_32x32x16_bf16 v[18:33], v[150:153], v[198:201], v[18:33]
	ds_read_b64_tr_b16 v[198:199], v158 offset:0x5400
	ds_read_b64_tr_b16 v[200:201], v158 offset:0x5c00
	s_waitcnt lgkmcnt(6)
	v_mfma_f32_32x32x16_bf16 v[18:33], v[186:189], v[202:205], v[18:33]
	ds_read_b64_tr_b16 v[202:203], v158 offset:0x6400
	ds_read_b64_tr_b16 v[204:205], v158 offset:0x6c00
	s_waitcnt lgkmcnt(6)
	v_mfma_f32_32x32x16_bf16 v[18:33], v[190:193], v[206:209], v[18:33]
	ds_read_b64_tr_b16 v[206:207], v158 offset:0x7400
	ds_read_b64_tr_b16 v[208:209], v158 offset:0x7c00
	s_waitcnt lgkmcnt(6)
	v_mfma_f32_32x32x16_bf16 v[34:49], v[146:149], v[194:197], v[34:49]
	ds_read_b64_tr_b16 v[194:195], v158 offset:0x4600
	ds_read_b64_tr_b16 v[196:197], v158 offset:0x4e00
	s_waitcnt lgkmcnt(6)
	v_mfma_f32_32x32x16_bf16 v[34:49], v[150:153], v[198:201], v[34:49]
	ds_read_b64_tr_b16 v[198:199], v158 offset:0x5600
	ds_read_b64_tr_b16 v[200:201], v158 offset:0x5e00
	s_waitcnt lgkmcnt(6)
	v_mfma_f32_32x32x16_bf16 v[34:49], v[186:189], v[202:205], v[34:49]
	ds_read_b64_tr_b16 v[202:203], v158 offset:0x6600
	ds_read_b64_tr_b16 v[204:205], v158 offset:0x6e00
	s_waitcnt lgkmcnt(6)
	v_mfma_f32_32x32x16_bf16 v[34:49], v[190:193], v[206:209], v[34:49]
	ds_read_b64_tr_b16 v[206:207], v158 offset:0x7600
	ds_read_b64_tr_b16 v[208:209], v158 offset:0x7e00
	s_waitcnt lgkmcnt(6)
	v_mfma_f32_32x32x16_bf16 v[50:65], v[146:149], v[194:197], v[50:65]
	s_waitcnt lgkmcnt(4)
	v_mfma_f32_32x32x16_bf16 v[50:65], v[150:153], v[198:201], v[50:65]
	s_waitcnt lgkmcnt(2)
	v_mfma_f32_32x32x16_bf16 v[50:65], v[186:189], v[202:205], v[50:65]
	s_waitcnt lgkmcnt(0)
	v_mfma_f32_32x32x16_bf16 v[50:65], v[190:193], v[206:209], v[50:65]
	v_max_f32_e32 v146, v83, v83
	v_max_f32_e32 v147, v82, v82
	v_max_f32_e32 v146, v147, v146
	v_max3_f32 v146, v146, v84, v85
	v_max3_f32 v146, v146, v86, v87
	v_max3_f32 v146, v146, v88, v89
	v_max3_f32 v146, v146, v90, v91
	v_max3_f32 v146, v146, v92, v93
	v_max3_f32 v146, v146, v94, v95
	v_max3_f32 v146, v146, v96, v97
	v_max3_f32 v146, v146, v66, v67
	v_max3_f32 v146, v146, v68, v69
	v_max3_f32 v146, v146, v70, v71
	v_max3_f32 v146, v146, v72, v73
	v_max3_f32 v146, v146, v74, v75
	v_max3_f32 v146, v146, v76, v77
	v_max3_f32 v146, v146, v78, v79
	v_max3_f32 v146, v146, v80, v81
	v_mov_b32_e32 v147, v146
	s_nop 1
	v_permlane32_swap_b32_e32 v146, v147
	v_max_f32_e32 v147, v147, v147
	v_max_f32_e32 v146, v146, v146
	v_max_f32_e32 v146, v146, v147
	v_sub_f32_e32 v147, v146, v184
	v_mul_f32_e32 v147, 0x3e0293ee, v147
	v_cmp_ge_f32_e32 vcc, s24, v147
	v_max_f32_e32 v147, v184, v184
	v_max_f32_e32 v147, v147, v146
	v_sub_f32_e32 v146, v184, v147
	v_mul_f32_e32 v146, 0x3e0293ee, v146
	v_exp_f32_e32 v146, v146
	s_cmp_eq_u64 vcc, exec
	s_cselect_b64 s[40:41], -1, 0
	v_cndmask_b32_e64 v146, v146, 1.0, s[40:41]
	v_cmp_gt_f32_e32 vcc, 1.0, v146
	s_barrier
	s_waitcnt vmcnt(1)
	ds_write_b128 v165, v[138:141] offset:49152
	s_waitcnt vmcnt(0)
	ds_write_b128 v165, v[142:145] offset:57344
	ds_write_b128 v166, v[130:133] offset:16384
	ds_write_b128 v167, v[134:137] offset:16384
	s_cbranch_vccz .LBB0_1422
	s_and_saveexec_b64 s[4:5], s[38:39]
	ds_write_b32 v159, v146 offset:128
	s_or_b64 exec, exec, s[4:5]
	s_waitcnt lgkmcnt(0)
	v_add_u32_e32 v142, s42, v162
	ds_read_b128 v[130:133], v142 offset:224
	ds_read_b128 v[134:137], v142 offset:192
	ds_read_b128 v[138:141], v142 offset:160
	ds_read_b128 v[142:145], v142 offset:128
	s_waitcnt lgkmcnt(3)
	v_pk_mul_f32 v[14:15], v[14:15], v[130:131]
	s_waitcnt lgkmcnt(2)
	v_pk_mul_f32 v[10:11], v[10:11], v[134:135]
	s_waitcnt lgkmcnt(1)
	v_pk_mul_f32 v[6:7], v[6:7], v[138:139]
	v_pk_mul_f32 v[16:17], v[16:17], v[132:133]
	v_pk_mul_f32 v[12:13], v[12:13], v[136:137]
	v_pk_mul_f32 v[8:9], v[8:9], v[140:141]
	s_waitcnt lgkmcnt(0)
	v_pk_mul_f32 v[4:5], v[4:5], v[144:145]
	v_pk_mul_f32 v[2:3], v[2:3], v[142:143]
	v_pk_mul_f32 v[30:31], v[30:31], v[130:131]
	v_pk_mul_f32 v[26:27], v[26:27], v[134:135]
	v_pk_mul_f32 v[22:23], v[22:23], v[138:139]
	v_pk_mul_f32 v[32:33], v[32:33], v[132:133]
	v_pk_mul_f32 v[28:29], v[28:29], v[136:137]
	v_pk_mul_f32 v[24:25], v[24:25], v[140:141]
	v_pk_mul_f32 v[20:21], v[20:21], v[144:145]
	v_pk_mul_f32 v[18:19], v[18:19], v[142:143]
	v_pk_mul_f32 v[46:47], v[46:47], v[130:131]
	v_pk_mul_f32 v[42:43], v[42:43], v[134:135]
	v_pk_mul_f32 v[38:39], v[38:39], v[138:139]
	v_pk_mul_f32 v[48:49], v[48:49], v[132:133]
	v_pk_mul_f32 v[44:45], v[44:45], v[136:137]
	v_pk_mul_f32 v[40:41], v[40:41], v[140:141]
	v_pk_mul_f32 v[36:37], v[36:37], v[144:145]
	v_pk_mul_f32 v[34:35], v[34:35], v[142:143]
	v_pk_mul_f32 v[62:63], v[62:63], v[130:131]
	v_pk_mul_f32 v[58:59], v[58:59], v[134:135]
	v_pk_mul_f32 v[54:55], v[54:55], v[138:139]
	v_pk_mul_f32 v[64:65], v[64:65], v[132:133]
	v_pk_mul_f32 v[60:61], v[60:61], v[136:137]
	v_pk_mul_f32 v[56:57], v[56:57], v[140:141]
	v_pk_mul_f32 v[52:53], v[52:53], v[144:145]
	v_pk_mul_f32 v[50:51], v[50:51], v[142:143]
